# phase overlap: weight conversion of layer l+1 done by the idle workgroups (128-255) in the FFN1-down tail of layer l; phase 0 converts layer 0 only (shared hand-written wide transposer)
# speedup vs baseline: 1.0038x; 1.0038x over previous
; #define LAS __attribute__((address_space(3)))
; __device__ __forceinline__ int tid_opaque() { int t = threadIdx.x; asm volatile("" : "+v"(t)); return t; }
; __device__ __forceinline__ int bid_opaque() { int b = blockIdx.x; asm volatile("" : "+s"(b)); return b; }
; __device__ __forceinline__ void tr_job(LAS float* tl, const float* src, int ld_src, int K, int Nout, bf16_t* dst, int ld_dst, int dkofs, int mode) {
;     const int tid = tid_opaque();
;     const int nkt = K / 64, ntl = nkt * (Nout / 64), G = gridDim.x;
;     const int ln = tid & 63, lk = tid >> 6, sk2 = (tid & 31) * 2, sn = tid >> 5;
;     float r[8];
;     int t = bid_opaque();
;     auto src_ptr = [&](int tt) -> const float* {
;         const int kt = tt % nkt, n0 = (tt / nkt) * 64; int c0 = n0;
;         if (mode == 1) { const int pn = n0 >> 8, rr = n0 & 255; c0 = (rr < 128) ? pn * 128 + rr : DFF + pn * 128 + (rr - 128); }
;         return src + (size_t)(kt * 64 + lk) * ld_src + c0 + ln; };
;     if (t < ntl) { const float* sp = src_ptr(t);
; #pragma unroll
;         for (int i = 0; i < 8; ++i) r[i] = sp[(size_t)(8 * i) * ld_src]; }
; __device__ void phase_setup(const Params& p, LAS unsigned char* lds) {
;     ...
;     for (int l = 0; l < NL; ++l) {
;         bf16_t* W = WT + (size_t)l * W_LAYER;
;         for (int j = 0; j < 2; ++j) {
;             tr_job(tl, p.in[I_FFNIN] + ((size_t)l * 2 + j) * D * (2 * DFF), 2 * DFF, D, 2 * DFF, W + (j ? W_FIN1 : W_FIN0), D, 0, 1);
;             tr_job(tl, p.in[I_FFNOUT] + ((size_t)l * 2 + j) * DFF * D, D, DFF, D, W + (j ? W_FOUT1 : W_FOUT0), DFF, 0, 0);
;         }
;         tr_job(tl, p.in[I_WIN] + (size_t)l * D * PROJ, PROJ, D, PROJ, W + W_WIN, D, 0, 0);
;         tr_job(tl, p.in[I_WBC] + (size_t)l * 256 * D, D, 256, D, W + W_WB, D, 0, 0);
;         tr_job(tl, p.in[I_WBG] + (size_t)l * 256 * D, D, 256, D, W + W_WB, D, 256, 0);
;         tr_job(tl, p.in[I_WBA] + (size_t)l * 512 * D, D, 512, D, W + W_WB, D, 512, 0);
;         tr_job(tl, p.in[I_WOUT] + (size_t)l * D * D, D, D, D, W + W_WO, D, 0, 0);
.LBB0_383:
	s_and_b64 vcc, exec, s[0:1]
	s_cbranch_vccz .LBB0_466
	s_waitcnt vmcnt(0)
	s_load_dword s10, s[94:95], 0x0
	s_waitcnt lgkmcnt(0)
	s_max_u32 s10, s10, 1
	s_mov_b32 s15, 24064
	s_cmp_eq_u32 s10, 256
	s_cselect_b32 s15, 6016, s15
	s_mov_b32 s11, s2
	s_mov_b32 s86, 0
.Lmytr_entry:
	v_lshrrev_b32_e32 v2, 4, v218
	v_and_b32_e32 v3, 15, v218
	v_lshlrev_b32_e32 v4, 4, v3
	v_mul_u32_u24_e32 v5, 260, v2
	v_lshl_add_u32 v5, v3, 4, v5
	v_lshrrev_b32_e32 v6, 3, v218
	v_and_b32_e32 v7, 7, v218
	v_mul_u32_u24_e32 v8, 2080, v7
	v_lshl_add_u32 v8, v6, 2, v8
	v_lshlrev_b32_e32 v9, 4, v7
	s_mov_b32 s13, 0
	s_cmp_lt_u32 s11, s15
	s_cbranch_scc0 .Lmytr_done
	s_mov_b32 s14, s11
	s_cmp_lt_u32 s14, s15
	s_cbranch_scc1 .Lmytr_pd0
	s_mov_b32 s13, 1
	s_branch .Lmytr_pe0
.Lmytr_pd0:
	s_mov_b32 s20, 0
	s_mov_b32 s21, s14
	s_cmp_ge_u32 s21, 6016
	s_cselect_b32 s0, 6016, 0
	s_cselect_b32 s1, 1, 0
	s_sub_u32 s21, s21, s0
	s_add_u32 s20, s20, s1
	s_cmp_ge_u32 s21, 6016
	s_cselect_b32 s0, 6016, 0
	s_cselect_b32 s1, 1, 0
	s_sub_u32 s21, s21, s0
	s_add_u32 s20, s20, s1
	s_cmp_ge_u32 s21, 6016
	s_cselect_b32 s0, 6016, 0
	s_cselect_b32 s1, 1, 0
	s_sub_u32 s21, s21, s0
	s_add_u32 s20, s20, s1
	s_mul_i32 s0, s20, 0x2f20000
	s_mul_hi_u32 s1, s20, 0x2f20000
	s_add_u32 s22, s42, s0
	s_addc_u32 s23, s43, s1
	s_lshl_b32 s29, s20, 1
	s_cmp_lt_u32 s21, 1408
	s_cbranch_scc1 .Lmytr_job0_p0
	s_cmp_lt_u32 s21, 2112
	s_cbranch_scc1 .Lmytr_job1_p0
	s_cmp_lt_u32 s21, 3520
	s_cbranch_scc1 .Lmytr_job2_p0
	s_cmp_lt_u32 s21, 4224
	s_cbranch_scc1 .Lmytr_job3_p0
	s_cmp_lt_u32 s21, 5504
	s_cbranch_scc1 .Lmytr_job4_p0
	s_cmp_lt_u32 s21, 5568
	s_cbranch_scc1 .Lmytr_job5_p0
	s_cmp_lt_u32 s21, 5632
	s_cbranch_scc1 .Lmytr_job6_p0
	s_cmp_lt_u32 s21, 5760
	s_cbranch_scc1 .Lmytr_job7_p0
	s_sub_u32 s12, s21, 5760
	s_movk_i32 s17, 0xb0
	s_mul_i32 s18, s20, 0x400000
	s_movk_i32 s6, 0x1000
	s_movk_i32 s28, 4
	s_movk_i32 s25, 0
	s_mov_b32 s24, 0x2d00000
	s_movk_i32 s7, 0x800
	s_branch .Lmytr_jobdone_p0
.Lmytr_job7_p0:
	s_sub_u32 s12, s21, 5632
	s_movk_i32 s17, 0xa8
	s_mul_i32 s18, s20, 0x200000
	s_movk_i32 s6, 0x1000
	s_movk_i32 s28, 3
	s_movk_i32 s25, 0
	s_mov_b32 s24, 0x2b00400
	s_movk_i32 s7, 0x800
	s_branch .Lmytr_jobdone_p0
.Lmytr_job6_p0:
	s_sub_u32 s12, s21, 5568
	s_movk_i32 s17, 0xa0
	s_mul_i32 s18, s20, 0x100000
	s_movk_i32 s6, 0x1000
	s_movk_i32 s28, 2
	s_movk_i32 s25, 0
	s_mov_b32 s24, 0x2b00200
	s_movk_i32 s7, 0x800
	s_branch .Lmytr_jobdone_p0
.Lmytr_job5_p0:
	s_sub_u32 s12, s21, 5504
	s_movk_i32 s17, 0x98
	s_mul_i32 s18, s20, 0x100000
	s_movk_i32 s6, 0x1000
	s_movk_i32 s28, 2
	s_movk_i32 s25, 0
	s_mov_b32 s24, 0x2b00000
	s_movk_i32 s7, 0x800
	s_branch .Lmytr_jobdone_p0
.Lmytr_job4_p0:
	s_sub_u32 s12, s21, 4224
	s_movk_i32 s17, 0x48
	s_mul_i32 s18, s20, 0x1400000
	s_movk_i32 s6, 0x5000
	s_movk_i32 s28, 4
	s_movk_i32 s25, 0
	s_mov_b32 s24, 0x2100000
	s_movk_i32 s7, 0x800
	s_branch .Lmytr_jobdone_p0
.Lmytr_job3_p0:
	s_sub_u32 s12, s21, 3520
	s_movk_i32 s17, 0x40
	s_add_u32 s0, s29, 1
	s_mul_i32 s18, s0, 0xb00000
	s_movk_i32 s6, 0x1000
	s_movk_i32 s28, 255
	s_movk_i32 s25, 0
	s_mov_b32 s24, 0x1b80000
	s_movk_i32 s7, 0x1600
	s_branch .Lmytr_jobdone_p0
.Lmytr_job2_p0:
	s_sub_u32 s12, s21, 2112
	s_movk_i32 s17, 0x38
	s_add_u32 s0, s29, 1
	s_mul_i32 s18, s0, 0x1600000
	s_movk_i32 s6, 0x5800
	s_movk_i32 s28, 4
	s_movk_i32 s25, 1
	s_mov_b32 s24, 0xb00000
	s_movk_i32 s7, 0x800
	s_branch .Lmytr_jobdone_p0
.Lmytr_job1_p0:
	s_sub_u32 s12, s21, 1408
	s_movk_i32 s17, 0x40
	s_mul_i32 s18, s29, 0xb00000
	s_movk_i32 s6, 0x1000
	s_movk_i32 s28, 255
	s_movk_i32 s25, 0
	s_mov_b32 s24, 0x1600000
	s_movk_i32 s7, 0x1600
	s_branch .Lmytr_jobdone_p0
.Lmytr_job0_p0:
	s_sub_u32 s12, s21, 0
	s_movk_i32 s17, 0x38
	s_mul_i32 s18, s29, 0x1600000
	s_movk_i32 s6, 0x5800
	s_movk_i32 s28, 4
	s_movk_i32 s25, 1
	s_mov_b32 s24, 0x0
	s_movk_i32 s7, 0x800
.Lmytr_jobdone_p0:
	s_nop 0
	s_load_dwordx2 s[4:5], s[36:37], s17
	s_cmp_eq_u32 s28, 255
	s_cbranch_scc1 .Lmytr_d44_p0
	s_lshr_b32 s30, s12, s28
	s_lshl_b32 s0, s30, s28
	s_sub_u32 s19, s12, s0
	s_branch .Lmytr_dd_p0
.Lmytr_d44_p0:
	s_mul_i32 s0, s12, 1490
	s_lshr_b32 s30, s0, 16
	s_mul_i32 s0, s30, 44
	s_sub_u32 s19, s12, s0
.Lmytr_dd_p0:
	s_lshl_b32 s30, s30, 6
	s_mov_b32 s31, s30
	s_cmp_eq_u32 s25, 0
	s_cbranch_scc1 .Lmytr_m0_p0
	s_lshr_b32 s0, s30, 8
	s_lshl_b32 s0, s0, 7
	s_and_b32 s1, s30, 127
	s_add_u32 s31, s0, s1
	s_and_b32 s1, s30, 128
	s_cmp_lg_u32 s1, 0
	s_cselect_b32 s1, 2816, 0
	s_add_u32 s31, s31, s1
.Lmytr_m0_p0:
	s_lshl_b32 s0, s19, 6
	s_mul_i32 s0, s0, s6
	s_lshl_b32 s1, s31, 2
	s_add_u32 s0, s0, s1
	s_waitcnt lgkmcnt(0)
	s_add_u32 s4, s4, s18
	s_addc_u32 s5, s5, 0
	s_add_u32 s4, s4, s0
	s_addc_u32 s5, s5, 0
	s_mul_i32 s0, s30, s7
	s_lshl_b32 s1, s19, 7
	s_add_u32 s0, s0, s1
	s_add_u32 s0, s0, s24
	s_add_u32 s8, s22, s0
	s_addc_u32 s9, s23, 0
	v_mad_u32_u24 v18, v2, s6, v4
	s_lshl_b32 s0, s6, 5
	v_add_u32_e32 v19, s0, v18
	global_load_dwordx4 v[32:35], v18, s[4:5]
	global_load_dwordx4 v[36:39], v19, s[4:5]
	v_mad_u32_u24 v0, v6, s7, v9
	v_lshl_add_u64 v[40:41], s[8:9], 0, v[0:1]
.Lmytr_pe0:
	s_add_u32 s14, s14, s10
	s_cmp_lt_u32 s14, s15
	s_cbranch_scc1 .Lmytr_pd1
	s_mov_b32 s13, 1
	s_branch .Lmytr_pe1

; __device__ __forceinline__ void tr_job(LAS float* tl, const float* src, int ld_src, int K, int Nout, bf16_t* dst, int ld_dst, int dkofs, int mode) {
;     ...
;     auto src_ptr = [&](int tt) -> const float* {
;         const int kt = tt % nkt, n0 = (tt / nkt) * 64; int c0 = n0;
;         if (mode == 1) { const int pn = n0 >> 8, rr = n0 & 255; c0 = (rr < 128) ? pn * 128 + rr : DFF + pn * 128 + (rr - 128); }
;         return src + (size_t)(kt * 64 + lk) * ld_src + c0 + ln; };
;     if (t < ntl) { const float* sp = src_ptr(t);
; #pragma unroll
;         for (int i = 0; i < 8; ++i) r[i] = sp[(size_t)(8 * i) * ld_src]; }
.Lmytr_m0_p1:
	s_lshl_b32 s0, s19, 6
	s_mul_i32 s0, s0, s6
	s_lshl_b32 s1, s31, 2
	s_add_u32 s0, s0, s1
	s_waitcnt lgkmcnt(0)
	s_add_u32 s4, s4, s18
	s_addc_u32 s5, s5, 0
	s_add_u32 s4, s4, s0
	s_addc_u32 s5, s5, 0
	s_mul_i32 s0, s30, s7
	s_lshl_b32 s1, s19, 7
	s_add_u32 s0, s0, s1
	s_add_u32 s0, s0, s24
	s_add_u32 s8, s22, s0
	s_addc_u32 s9, s23, 0
	v_mad_u32_u24 v18, v2, s6, v4
	s_lshl_b32 s0, s6, 5
	v_add_u32_e32 v19, s0, v18
	global_load_dwordx4 v[44:47], v18, s[4:5]
	global_load_dwordx4 v[48:51], v19, s[4:5]
	v_mad_u32_u24 v0, v6, s7, v9
	v_lshl_add_u64 v[52:53], s[8:9], 0, v[0:1]

; __device__ __forceinline__ void tr_job(LAS float* tl, const float* src, int ld_src, int K, int Nout, bf16_t* dst, int ld_dst, int dkofs, int mode) {
;     ...
;     auto src_ptr = [&](int tt) -> const float* {
;         const int kt = tt % nkt, n0 = (tt / nkt) * 64; int c0 = n0;
;         if (mode == 1) { const int pn = n0 >> 8, rr = n0 & 255; c0 = (rr < 128) ? pn * 128 + rr : DFF + pn * 128 + (rr - 128); }
;         return src + (size_t)(kt * 64 + lk) * ld_src + c0 + ln; };
;     if (t < ntl) { const float* sp = src_ptr(t);
; #pragma unroll
;         for (int i = 0; i < 8; ++i) r[i] = sp[(size_t)(8 * i) * ld_src]; }
.Lmytr_m0_p2:
	s_lshl_b32 s0, s19, 6
	s_mul_i32 s0, s0, s6
	s_lshl_b32 s1, s31, 2
	s_add_u32 s0, s0, s1
	s_waitcnt lgkmcnt(0)
	s_add_u32 s4, s4, s18
	s_addc_u32 s5, s5, 0
	s_add_u32 s4, s4, s0
	s_addc_u32 s5, s5, 0
	s_mul_i32 s0, s30, s7
	s_lshl_b32 s1, s19, 7
	s_add_u32 s0, s0, s1
	s_add_u32 s0, s0, s24
	s_add_u32 s8, s22, s0
	s_addc_u32 s9, s23, 0
	v_mad_u32_u24 v18, v2, s6, v4
	s_lshl_b32 s0, s6, 5
	v_add_u32_e32 v19, s0, v18
	global_load_dwordx4 v[56:59], v18, s[4:5]
	global_load_dwordx4 v[60:63], v19, s[4:5]
	v_mad_u32_u24 v0, v6, s7, v9
	v_lshl_add_u64 v[64:65], s[8:9], 0, v[0:1]

; __device__ __forceinline__ void tr_job(LAS float* tl, const float* src, int ld_src, int K, int Nout, bf16_t* dst, int ld_dst, int dkofs, int mode) {
;     ...
;     auto src_ptr = [&](int tt) -> const float* {
;         const int kt = tt % nkt, n0 = (tt / nkt) * 64; int c0 = n0;
;         if (mode == 1) { const int pn = n0 >> 8, rr = n0 & 255; c0 = (rr < 128) ? pn * 128 + rr : DFF + pn * 128 + (rr - 128); }
;         return src + (size_t)(kt * 64 + lk) * ld_src + c0 + ln; };
;     if (t < ntl) { const float* sp = src_ptr(t);
; #pragma unroll
;         for (int i = 0; i < 8; ++i) r[i] = sp[(size_t)(8 * i) * ld_src]; }
.Lmytr_m0_p3:
	s_lshl_b32 s0, s19, 6
	s_mul_i32 s0, s0, s6
	s_lshl_b32 s1, s31, 2
	s_add_u32 s0, s0, s1
	s_waitcnt lgkmcnt(0)
	s_add_u32 s4, s4, s18
	s_addc_u32 s5, s5, 0
	s_add_u32 s4, s4, s0
	s_addc_u32 s5, s5, 0
	s_mul_i32 s0, s30, s7
	s_lshl_b32 s1, s19, 7
	s_add_u32 s0, s0, s1
	s_add_u32 s0, s0, s24
	s_add_u32 s8, s22, s0
	s_addc_u32 s9, s23, 0
	v_mad_u32_u24 v18, v2, s6, v4
	s_lshl_b32 s0, s6, 5
	v_add_u32_e32 v19, s0, v18
	global_load_dwordx4 v[68:71], v18, s[4:5]
	global_load_dwordx4 v[72:75], v19, s[4:5]
	v_mad_u32_u24 v0, v6, s7, v9
	v_lshl_add_u64 v[76:77], s[8:9], 0, v[0:1]

; __device__ __forceinline__ void tr_job(LAS float* tl, const float* src, int ld_src, int K, int Nout, bf16_t* dst, int ld_dst, int dkofs, int mode) {
;     ...
;     auto src_ptr = [&](int tt) -> const float* {
;         const int kt = tt % nkt, n0 = (tt / nkt) * 64; int c0 = n0;
;         if (mode == 1) { const int pn = n0 >> 8, rr = n0 & 255; c0 = (rr < 128) ? pn * 128 + rr : DFF + pn * 128 + (rr - 128); }
;         return src + (size_t)(kt * 64 + lk) * ld_src + c0 + ln; };
;     if (t < ntl) { const float* sp = src_ptr(t);
; #pragma unroll
;         for (int i = 0; i < 8; ++i) r[i] = sp[(size_t)(8 * i) * ld_src]; }
.Lmytr_m0_p4:
	s_lshl_b32 s0, s19, 6
	s_mul_i32 s0, s0, s6
	s_lshl_b32 s1, s31, 2
	s_add_u32 s0, s0, s1
	s_waitcnt lgkmcnt(0)
	s_add_u32 s4, s4, s18
	s_addc_u32 s5, s5, 0
	s_add_u32 s4, s4, s0
	s_addc_u32 s5, s5, 0
	s_mul_i32 s0, s30, s7
	s_lshl_b32 s1, s19, 7
	s_add_u32 s0, s0, s1
	s_add_u32 s0, s0, s24
	s_add_u32 s8, s22, s0
	s_addc_u32 s9, s23, 0
	v_mad_u32_u24 v18, v2, s6, v4
	s_lshl_b32 s0, s6, 5
	v_add_u32_e32 v19, s0, v18
	global_load_dwordx4 v[80:83], v18, s[4:5]
	global_load_dwordx4 v[84:87], v19, s[4:5]
	v_mad_u32_u24 v0, v6, s7, v9
	v_lshl_add_u64 v[88:89], s[8:9], 0, v[0:1]

; __device__ __forceinline__ unsigned cvt_pk_bf16(float lo, float hi) { unsigned r; asm volatile("v_cvt_pk_bf16_f32 %0, %1, %2" : "=v"(r) : "v"(lo), "v"(hi)); return r; }
; __device__ __forceinline__ void tr_job(LAS float* tl, const float* src, int ld_src, int K, int Nout, bf16_t* dst, int ld_dst, int dkofs, int mode) {
;     ...
;     for (; t < ntl; t += G) {
; #pragma unroll
;         for (int i = 0; i < 8; ++i) tl[(lk + 8 * i) * 65 + ln] = r[i];
;         __syncthreads();
;         if (t + G < ntl) { const float* sp = src_ptr(t + G);
; #pragma unroll
;             for (int i = 0; i < 8; ++i) r[i] = sp[(size_t)(8 * i) * ld_src]; }
;         { const int kt = t % nkt, n0 = (t / nkt) * 64;
; #pragma unroll
;           for (int i = 0; i < 4; ++i) { const int n = sn + 16 * i; *(unsigned*)(dst + (size_t)(n0 + n) * ld_dst + dkofs + kt * 64 + sk2) = cvt_pk_bf16(tl[sk2 * 65 + n], tl[(sk2 + 1) * 65 + n]); } }
;         __syncthreads();
;     }
.Lmytr_m0_p5:
	s_lshl_b32 s0, s19, 6
	s_mul_i32 s0, s0, s6
	s_lshl_b32 s1, s31, 2
	s_add_u32 s0, s0, s1
	s_waitcnt lgkmcnt(0)
	s_add_u32 s4, s4, s18
	s_addc_u32 s5, s5, 0
	s_add_u32 s4, s4, s0
	s_addc_u32 s5, s5, 0
	s_mul_i32 s0, s30, s7
	s_lshl_b32 s1, s19, 7
	s_add_u32 s0, s0, s1
	s_add_u32 s0, s0, s24
	s_add_u32 s8, s22, s0
	s_addc_u32 s9, s23, 0
	v_mad_u32_u24 v18, v2, s6, v4
	s_lshl_b32 s0, s6, 5
	v_add_u32_e32 v19, s0, v18
	global_load_dwordx4 v[92:95], v18, s[4:5]
	global_load_dwordx4 v[96:99], v19, s[4:5]
	v_mad_u32_u24 v0, v6, s7, v9
	v_lshl_add_u64 v[100:101], s[8:9], 0, v[0:1]
.Lmytr_pe5:
	s_add_u32 s14, s14, s10
.Lmytr_loop:
	s_cmp_lt_u32 s11, s15
	s_cbranch_scc0 .Lmytr_done
	s_cmp_eq_u32 s13, 0
	s_cbranch_scc1 .Lmytr_wf0
	s_waitcnt vmcnt(0)
	s_branch .Lmytr_wg0
.Lmytr_wf0:
	s_waitcnt vmcnt(10)
.Lmytr_wg0:
	ds_write_b32 v5, v32
	ds_write_b32 v5, v33 offset:4
	ds_write_b32 v5, v34 offset:8
	ds_write_b32 v5, v35 offset:12
	ds_write_b32 v5, v36 offset:8320
	ds_write_b32 v5, v37 offset:8324
	ds_write_b32 v5, v38 offset:8328
	ds_write_b32 v5, v39 offset:8332
	s_waitcnt lgkmcnt(0)
	s_barrier
	ds_read_b32 v20, v8
	ds_read_b32 v21, v8 offset:260
	ds_read_b32 v22, v8 offset:520
	ds_read_b32 v23, v8 offset:780
	ds_read_b32 v24, v8 offset:1040
	ds_read_b32 v25, v8 offset:1300
	ds_read_b32 v26, v8 offset:1560
	ds_read_b32 v27, v8 offset:1820
	s_waitcnt lgkmcnt(0)
	v_cvt_pk_bf16_f32 v28, v20, v21
	v_cvt_pk_bf16_f32 v29, v22, v23
	v_cvt_pk_bf16_f32 v30, v24, v25
	v_cvt_pk_bf16_f32 v31, v26, v27
	global_store_dwordx4 v[40:41], v[28:31], off
	s_mul_i32 s14, s10, 6
	s_add_u32 s14, s14, s11
	s_cmp_lt_u32 s14, s15
	s_cbranch_scc1 .Lmytr_ld0
	s_mov_b32 s13, 1
	s_branch .Lmytr_le0

; __device__ __forceinline__ unsigned cvt_pk_bf16(float lo, float hi) { unsigned r; asm volatile("v_cvt_pk_bf16_f32 %0, %1, %2" : "=v"(r) : "v"(lo), "v"(hi)); return r; }
; __device__ __forceinline__ void tr_job(LAS float* tl, const float* src, int ld_src, int K, int Nout, bf16_t* dst, int ld_dst, int dkofs, int mode) {
;     ...
;     for (; t < ntl; t += G) {
; #pragma unroll
;         for (int i = 0; i < 8; ++i) tl[(lk + 8 * i) * 65 + ln] = r[i];
;         __syncthreads();
;         if (t + G < ntl) { const float* sp = src_ptr(t + G);
; #pragma unroll
;             for (int i = 0; i < 8; ++i) r[i] = sp[(size_t)(8 * i) * ld_src]; }
;         { const int kt = t % nkt, n0 = (t / nkt) * 64;
; #pragma unroll
;           for (int i = 0; i < 4; ++i) { const int n = sn + 16 * i; *(unsigned*)(dst + (size_t)(n0 + n) * ld_dst + dkofs + kt * 64 + sk2) = cvt_pk_bf16(tl[sk2 * 65 + n], tl[(sk2 + 1) * 65 + n]); } }
;         __syncthreads();
;     }
.Lmytr_le0:
	s_barrier
	s_add_u32 s11, s11, s10
	s_cmp_lt_u32 s11, s15
	s_cbranch_scc0 .Lmytr_done
	s_cmp_eq_u32 s13, 0
	s_cbranch_scc1 .Lmytr_wf1
	s_waitcnt vmcnt(0)
	s_branch .Lmytr_wg1

; __device__ __forceinline__ unsigned cvt_pk_bf16(float lo, float hi) { unsigned r; asm volatile("v_cvt_pk_bf16_f32 %0, %1, %2" : "=v"(r) : "v"(lo), "v"(hi)); return r; }
; __device__ __forceinline__ void tr_job(LAS float* tl, const float* src, int ld_src, int K, int Nout, bf16_t* dst, int ld_dst, int dkofs, int mode) {
;     ...
;     for (; t < ntl; t += G) {
; #pragma unroll
;         for (int i = 0; i < 8; ++i) tl[(lk + 8 * i) * 65 + ln] = r[i];
;         __syncthreads();
;         if (t + G < ntl) { const float* sp = src_ptr(t + G);
; #pragma unroll
;             for (int i = 0; i < 8; ++i) r[i] = sp[(size_t)(8 * i) * ld_src]; }
;         { const int kt = t % nkt, n0 = (t / nkt) * 64;
; #pragma unroll
;           for (int i = 0; i < 4; ++i) { const int n = sn + 16 * i; *(unsigned*)(dst + (size_t)(n0 + n) * ld_dst + dkofs + kt * 64 + sk2) = cvt_pk_bf16(tl[sk2 * 65 + n], tl[(sk2 + 1) * 65 + n]); } }
;         __syncthreads();
;     }
.Lmytr_wg1:
	ds_write_b32 v5, v44
	ds_write_b32 v5, v45 offset:4
	ds_write_b32 v5, v46 offset:8
	ds_write_b32 v5, v47 offset:12
	ds_write_b32 v5, v48 offset:8320
	ds_write_b32 v5, v49 offset:8324
	ds_write_b32 v5, v50 offset:8328
	ds_write_b32 v5, v51 offset:8332
	s_waitcnt lgkmcnt(0)
	s_barrier
	ds_read_b32 v20, v8
	ds_read_b32 v21, v8 offset:260
	ds_read_b32 v22, v8 offset:520
	ds_read_b32 v23, v8 offset:780
	ds_read_b32 v24, v8 offset:1040
	ds_read_b32 v25, v8 offset:1300
	ds_read_b32 v26, v8 offset:1560
	ds_read_b32 v27, v8 offset:1820
	s_waitcnt lgkmcnt(0)
	v_cvt_pk_bf16_f32 v28, v20, v21
	v_cvt_pk_bf16_f32 v29, v22, v23
	v_cvt_pk_bf16_f32 v30, v24, v25
	v_cvt_pk_bf16_f32 v31, v26, v27
	global_store_dwordx4 v[52:53], v[28:31], off
	s_mul_i32 s14, s10, 6
	s_add_u32 s14, s14, s11
	s_cmp_lt_u32 s14, s15
	s_cbranch_scc1 .Lmytr_ld1
	s_mov_b32 s13, 1
	s_branch .Lmytr_le1

; __device__ __forceinline__ unsigned cvt_pk_bf16(float lo, float hi) { unsigned r; asm volatile("v_cvt_pk_bf16_f32 %0, %1, %2" : "=v"(r) : "v"(lo), "v"(hi)); return r; }
; __device__ __forceinline__ void tr_job(LAS float* tl, const float* src, int ld_src, int K, int Nout, bf16_t* dst, int ld_dst, int dkofs, int mode) {
;     ...
;     for (; t < ntl; t += G) {
; #pragma unroll
;         for (int i = 0; i < 8; ++i) tl[(lk + 8 * i) * 65 + ln] = r[i];
;         __syncthreads();
;         if (t + G < ntl) { const float* sp = src_ptr(t + G);
; #pragma unroll
;             for (int i = 0; i < 8; ++i) r[i] = sp[(size_t)(8 * i) * ld_src]; }
;         { const int kt = t % nkt, n0 = (t / nkt) * 64;
; #pragma unroll
;           for (int i = 0; i < 4; ++i) { const int n = sn + 16 * i; *(unsigned*)(dst + (size_t)(n0 + n) * ld_dst + dkofs + kt * 64 + sk2) = cvt_pk_bf16(tl[sk2 * 65 + n], tl[(sk2 + 1) * 65 + n]); } }
;         __syncthreads();
;     }
.Lmytr_wg2:
	ds_write_b32 v5, v56
	ds_write_b32 v5, v57 offset:4
	ds_write_b32 v5, v58 offset:8
	ds_write_b32 v5, v59 offset:12
	ds_write_b32 v5, v60 offset:8320
	ds_write_b32 v5, v61 offset:8324
	ds_write_b32 v5, v62 offset:8328
	ds_write_b32 v5, v63 offset:8332
	s_waitcnt lgkmcnt(0)
	s_barrier
	ds_read_b32 v20, v8
	ds_read_b32 v21, v8 offset:260
	ds_read_b32 v22, v8 offset:520
	ds_read_b32 v23, v8 offset:780
	ds_read_b32 v24, v8 offset:1040
	ds_read_b32 v25, v8 offset:1300
	ds_read_b32 v26, v8 offset:1560
	ds_read_b32 v27, v8 offset:1820
	s_waitcnt lgkmcnt(0)
	v_cvt_pk_bf16_f32 v28, v20, v21
	v_cvt_pk_bf16_f32 v29, v22, v23
	v_cvt_pk_bf16_f32 v30, v24, v25
	v_cvt_pk_bf16_f32 v31, v26, v27
	global_store_dwordx4 v[64:65], v[28:31], off
	s_mul_i32 s14, s10, 6
	s_add_u32 s14, s14, s11
	s_cmp_lt_u32 s14, s15
	s_cbranch_scc1 .Lmytr_ld2
	s_mov_b32 s13, 1
	s_branch .Lmytr_le2

; __device__ __forceinline__ unsigned cvt_pk_bf16(float lo, float hi) { unsigned r; asm volatile("v_cvt_pk_bf16_f32 %0, %1, %2" : "=v"(r) : "v"(lo), "v"(hi)); return r; }
; __device__ __forceinline__ void tr_job(LAS float* tl, const float* src, int ld_src, int K, int Nout, bf16_t* dst, int ld_dst, int dkofs, int mode) {
;     ...
;     for (; t < ntl; t += G) {
; #pragma unroll
;         for (int i = 0; i < 8; ++i) tl[(lk + 8 * i) * 65 + ln] = r[i];
;         __syncthreads();
;         if (t + G < ntl) { const float* sp = src_ptr(t + G);
; #pragma unroll
;             for (int i = 0; i < 8; ++i) r[i] = sp[(size_t)(8 * i) * ld_src]; }
;         { const int kt = t % nkt, n0 = (t / nkt) * 64;
; #pragma unroll
;           for (int i = 0; i < 4; ++i) { const int n = sn + 16 * i; *(unsigned*)(dst + (size_t)(n0 + n) * ld_dst + dkofs + kt * 64 + sk2) = cvt_pk_bf16(tl[sk2 * 65 + n], tl[(sk2 + 1) * 65 + n]); } }
;         __syncthreads();
;     }
.Lmytr_wg3:
	ds_write_b32 v5, v68
	ds_write_b32 v5, v69 offset:4
	ds_write_b32 v5, v70 offset:8
	ds_write_b32 v5, v71 offset:12
	ds_write_b32 v5, v72 offset:8320
	ds_write_b32 v5, v73 offset:8324
	ds_write_b32 v5, v74 offset:8328
	ds_write_b32 v5, v75 offset:8332
	s_waitcnt lgkmcnt(0)
	s_barrier
	ds_read_b32 v20, v8
	ds_read_b32 v21, v8 offset:260
	ds_read_b32 v22, v8 offset:520
	ds_read_b32 v23, v8 offset:780
	ds_read_b32 v24, v8 offset:1040
	ds_read_b32 v25, v8 offset:1300
	ds_read_b32 v26, v8 offset:1560
	ds_read_b32 v27, v8 offset:1820
	s_waitcnt lgkmcnt(0)
	v_cvt_pk_bf16_f32 v28, v20, v21
	v_cvt_pk_bf16_f32 v29, v22, v23
	v_cvt_pk_bf16_f32 v30, v24, v25
	v_cvt_pk_bf16_f32 v31, v26, v27
	global_store_dwordx4 v[76:77], v[28:31], off
	s_mul_i32 s14, s10, 6
	s_add_u32 s14, s14, s11
	s_cmp_lt_u32 s14, s15
	s_cbranch_scc1 .Lmytr_ld3
	s_mov_b32 s13, 1
	s_branch .Lmytr_le3

; __device__ __forceinline__ unsigned cvt_pk_bf16(float lo, float hi) { unsigned r; asm volatile("v_cvt_pk_bf16_f32 %0, %1, %2" : "=v"(r) : "v"(lo), "v"(hi)); return r; }
; __device__ __forceinline__ void tr_job(LAS float* tl, const float* src, int ld_src, int K, int Nout, bf16_t* dst, int ld_dst, int dkofs, int mode) {
;     ...
;     for (; t < ntl; t += G) {
; #pragma unroll
;         for (int i = 0; i < 8; ++i) tl[(lk + 8 * i) * 65 + ln] = r[i];
;         __syncthreads();
;         if (t + G < ntl) { const float* sp = src_ptr(t + G);
; #pragma unroll
;             for (int i = 0; i < 8; ++i) r[i] = sp[(size_t)(8 * i) * ld_src]; }
;         { const int kt = t % nkt, n0 = (t / nkt) * 64;
; #pragma unroll
;           for (int i = 0; i < 4; ++i) { const int n = sn + 16 * i; *(unsigned*)(dst + (size_t)(n0 + n) * ld_dst + dkofs + kt * 64 + sk2) = cvt_pk_bf16(tl[sk2 * 65 + n], tl[(sk2 + 1) * 65 + n]); } }
;         __syncthreads();
;     }
.Lmytr_wg4:
	ds_write_b32 v5, v80
	ds_write_b32 v5, v81 offset:4
	ds_write_b32 v5, v82 offset:8
	ds_write_b32 v5, v83 offset:12
	ds_write_b32 v5, v84 offset:8320
	ds_write_b32 v5, v85 offset:8324
	ds_write_b32 v5, v86 offset:8328
	ds_write_b32 v5, v87 offset:8332
	s_waitcnt lgkmcnt(0)
	s_barrier
	ds_read_b32 v20, v8
	ds_read_b32 v21, v8 offset:260
	ds_read_b32 v22, v8 offset:520
	ds_read_b32 v23, v8 offset:780
	ds_read_b32 v24, v8 offset:1040
	ds_read_b32 v25, v8 offset:1300
	ds_read_b32 v26, v8 offset:1560
	ds_read_b32 v27, v8 offset:1820
	s_waitcnt lgkmcnt(0)
	v_cvt_pk_bf16_f32 v28, v20, v21
	v_cvt_pk_bf16_f32 v29, v22, v23
	v_cvt_pk_bf16_f32 v30, v24, v25
	v_cvt_pk_bf16_f32 v31, v26, v27
	global_store_dwordx4 v[88:89], v[28:31], off
	s_mul_i32 s14, s10, 6
	s_add_u32 s14, s14, s11
	s_cmp_lt_u32 s14, s15
	s_cbranch_scc1 .Lmytr_ld4
	s_mov_b32 s13, 1
	s_branch .Lmytr_le4

; __device__ __forceinline__ unsigned cvt_pk_bf16(float lo, float hi) { unsigned r; asm volatile("v_cvt_pk_bf16_f32 %0, %1, %2" : "=v"(r) : "v"(lo), "v"(hi)); return r; }
; __device__ __forceinline__ void tr_job(LAS float* tl, const float* src, int ld_src, int K, int Nout, bf16_t* dst, int ld_dst, int dkofs, int mode) {
;     ...
;     for (; t < ntl; t += G) {
; #pragma unroll
;         for (int i = 0; i < 8; ++i) tl[(lk + 8 * i) * 65 + ln] = r[i];
;         __syncthreads();
;         if (t + G < ntl) { const float* sp = src_ptr(t + G);
; #pragma unroll
;             for (int i = 0; i < 8; ++i) r[i] = sp[(size_t)(8 * i) * ld_src]; }
;         { const int kt = t % nkt, n0 = (t / nkt) * 64;
; #pragma unroll
;           for (int i = 0; i < 4; ++i) { const int n = sn + 16 * i; *(unsigned*)(dst + (size_t)(n0 + n) * ld_dst + dkofs + kt * 64 + sk2) = cvt_pk_bf16(tl[sk2 * 65 + n], tl[(sk2 + 1) * 65 + n]); } }
;         __syncthreads();
;     }
.Lmytr_wg5:
	ds_write_b32 v5, v92
	ds_write_b32 v5, v93 offset:4
	ds_write_b32 v5, v94 offset:8
	ds_write_b32 v5, v95 offset:12
	ds_write_b32 v5, v96 offset:8320
	ds_write_b32 v5, v97 offset:8324
	ds_write_b32 v5, v98 offset:8328
	ds_write_b32 v5, v99 offset:8332
	s_waitcnt lgkmcnt(0)
	s_barrier
	ds_read_b32 v20, v8
	ds_read_b32 v21, v8 offset:260
	ds_read_b32 v22, v8 offset:520
	ds_read_b32 v23, v8 offset:780
	ds_read_b32 v24, v8 offset:1040
	ds_read_b32 v25, v8 offset:1300
	ds_read_b32 v26, v8 offset:1560
	ds_read_b32 v27, v8 offset:1820
	s_waitcnt lgkmcnt(0)
	v_cvt_pk_bf16_f32 v28, v20, v21
	v_cvt_pk_bf16_f32 v29, v22, v23
	v_cvt_pk_bf16_f32 v30, v24, v25
	v_cvt_pk_bf16_f32 v31, v26, v27
	global_store_dwordx4 v[100:101], v[28:31], off
	s_mul_i32 s14, s10, 6
	s_add_u32 s14, s14, s11
	s_cmp_lt_u32 s14, s15
	s_cbranch_scc1 .Lmytr_ld5
	s_mov_b32 s13, 1
	s_branch .Lmytr_le5

; __device__ void phase_setup(const Params& p, LAS unsigned char* lds) {
;     ...
;     for (int l = 0; l < NL; ++l) {
;         bf16_t* W = WT + (size_t)l * W_LAYER;
;         for (int j = 0; j < 2; ++j) {
;             tr_job(tl, p.in[I_FFNIN] + ((size_t)l * 2 + j) * D * (2 * DFF), 2 * DFF, D, 2 * DFF, W + (j ? W_FIN1 : W_FIN0), D, 0, 1);
;             tr_job(tl, p.in[I_FFNOUT] + ((size_t)l * 2 + j) * DFF * D, D, DFF, D, W + (j ? W_FOUT1 : W_FOUT0), DFF, 0, 0);
;         }
;         tr_job(tl, p.in[I_WIN] + (size_t)l * D * PROJ, PROJ, D, PROJ, W + W_WIN, D, 0, 0);
;         tr_job(tl, p.in[I_WBC] + (size_t)l * 256 * D, D, 256, D, W + W_WB, D, 0, 0);
;         tr_job(tl, p.in[I_WBG] + (size_t)l * 256 * D, D, 256, D, W + W_WB, D, 256, 0);
;         tr_job(tl, p.in[I_WBA] + (size_t)l * 512 * D, D, 512, D, W + W_WB, D, 512, 0);
;         tr_job(tl, p.in[I_WOUT] + (size_t)l * D * D, D, D, D, W + W_WO, D, 0, 0);
.Lmytr_le5:
	s_barrier
	s_add_u32 s11, s11, s10
	s_branch .Lmytr_loop
.Lmytr_done:
	v_readlane_b32 s4, v254, 11
	v_readlane_b32 s5, v254, 12
	v_readlane_b32 s6, v254, 13
	v_readlane_b32 s7, v254, 14
	v_readlane_b32 s8, v254, 15
	v_readlane_b32 s9, v254, 16
	v_readlane_b32 s10, v254, 17
	v_readlane_b32 s11, v254, 18
	v_readlane_b32 s12, v254, 19
	v_readlane_b32 s13, v254, 20
	v_readlane_b32 s14, v254, 21
	v_readlane_b32 s15, v254, 22
	v_readlane_b32 s16, v254, 23
	v_readlane_b32 s17, v254, 24
	v_readlane_b32 s18, v254, 25
	v_readlane_b32 s19, v254, 26
	s_cmp_eq_u32 s86, 0
	s_cbranch_scc1 .Lmytr_ret0
	s_branch .Lmytr_ret1
.Lmytr_ret0:
	v_mov_b32_e32 v2, v218
	s_mov_b32 s86, 0
	v_lshlrev_b32_e32 v3, 1, v2
	s_mov_b32 s20, 0xdc000
	s_mov_b32 s21, 0x78000
	s_mov_b32 s22, 0x58000
	s_mov_b32 s23, 0x84000
	s_mov_b32 s24, 0xb0000
	s_mov_b32 s25, 0x108000
	s_mov_b32 s28, 0x134000
	s_movk_i32 s29, 0x104
	s_mov_b32 s30, 0x30000
	s_mov_b32 s31, 0x38000
	s_branch .LBB0_386

; #define LAS __attribute__((address_space(3)))
; __device__ __forceinline__ int tid_opaque() { int t = threadIdx.x; asm volatile("" : "+v"(t)); return t; }
; __device__ __forceinline__ int bid_opaque() { int b = blockIdx.x; asm volatile("" : "+s"(b)); return b; }
; __device__ __forceinline__ void tr_job(LAS float* tl, const float* src, int ld_src, int K, int Nout, bf16_t* dst, int ld_dst, int dkofs, int mode) {
;     const int tid = tid_opaque();
;     const int nkt = K / 64, ntl = nkt * (Nout / 64), G = gridDim.x;
;     const int ln = tid & 63, lk = tid >> 6, sk2 = (tid & 31) * 2, sn = tid >> 5;
;     float r[8];
;     int t = bid_opaque();
;     auto src_ptr = [&](int tt) -> const float* {
;         const int kt = tt % nkt, n0 = (tt / nkt) * 64; int c0 = n0;
;         if (mode == 1) { const int pn = n0 >> 8, rr = n0 & 255; c0 = (rr < 128) ? pn * 128 + rr : DFF + pn * 128 + (rr - 128); }
;         return src + (size_t)(kt * 64 + lk) * ld_src + c0 + ln; };
;     if (t < ntl) { const float* sp = src_ptr(t);
; #pragma unroll
;         for (int i = 0; i < 8; ++i) r[i] = sp[(size_t)(8 * i) * ld_src]; }
;     for (; t < ntl; t += G) {
; #pragma unroll
;         for (int i = 0; i < 8; ++i) tl[(lk + 8 * i) * 65 + ln] = r[i];
;         __syncthreads();
;         if (t + G < ntl) { const float* sp = src_ptr(t + G);
; #pragma unroll
;             for (int i = 0; i < 8; ++i) r[i] = sp[(size_t)(8 * i) * ld_src]; }
; __device__ void phase_setup(const Params& p, LAS unsigned char* lds) {
;     ...
;             tr_job(tl, p.in[I_FFNIN] + ((size_t)l * 2 + j) * D * (2 * DFF), 2 * DFF, D, 2 * DFF, W + (j ? W_FIN1 : W_FIN0), D, 0, 1);
.LBB0_386:
	v_mov_b32_e32 v4, v218
	s_waitcnt lgkmcnt(0)
	s_load_dword s10, s[94:95], 0x0
	s_mul_i32 s0, s86, 0x2f20000
	s_mul_hi_u32 s1, s86, 0x2f20000
	s_add_u32 s0, s42, s0
	s_addc_u32 s1, s43, s1
	s_mov_b32 s8, s2
	s_cmpk_lt_i32 s8, 0x580
	s_branch .LBB0_392
	v_readlane_b32 s52, v254, 11
	s_mul_i32 s4, s86, 0x2c00000
	v_readlane_b32 s66, v254, 25
	s_mul_hi_u32 s5, s86, 0x2c00000
	v_readlane_b32 s67, v254, 26
	s_add_u32 s4, s66, s4
	s_addc_u32 s5, s67, s5
	s_ashr_i32 s6, s8, 31
	s_lshr_b32 s6, s6, 28
	s_add_i32 s7, s8, s6
	s_ashr_i32 s6, s7, 4
	s_lshl_b32 s9, s6, 6
	s_lshl_b32 s6, s6, 5
	s_and_b32 s9, s9, 0xc0
	s_and_b32 s6, s6, 0xffffff80
	s_or_b32 s11, s6, s9
	s_add_i32 s6, s9, s6
	s_addk_i32 s6, 0xa80
	s_cmpk_lt_u32 s9, 0x80
	s_cselect_b32 s6, s11, s6
	s_and_b32 s7, s7, 0x3fffff0
	v_ashrrev_i32_e32 v19, 6, v4
	s_sub_i32 s7, s8, s7
	v_lshl_add_u32 v0, s7, 6, v19
	v_mov_b64_e32 v[6:7], s[4:5]
	v_and_b32_e32 v18, 63, v4
	v_mad_i64_i32 v[6:7], s[12:13], v0, s50, v[6:7]
	s_ashr_i32 s7, s6, 31
	v_lshl_add_u64 v[6:7], s[6:7], 2, v[6:7]
	v_lshlrev_b32_e32 v0, 2, v18
	v_lshl_add_u64 v[6:7], v[6:7], 0, v[0:1]
	v_add_co_u32_e32 v8, vcc, s49, v6
	s_waitcnt lgkmcnt(0)
	s_lshl_b32 s11, s10, 6
	v_addc_co_u32_e32 v9, vcc, 0, v7, vcc
	s_waitcnt vmcnt(9)
	v_add_co_u32_e32 v12, vcc, s22, v6
	s_lshl_b32 s9, s8, 6
	s_waitcnt vmcnt(8)
	v_addc_co_u32_e32 v13, vcc, 0, v7, vcc
	s_waitcnt vmcnt(7)
	v_add_co_u32_e32 v14, vcc, s23, v6
	v_readlane_b32 s53, v254, 12
	s_waitcnt vmcnt(6)
	v_addc_co_u32_e32 v15, vcc, 0, v7, vcc
	s_waitcnt vmcnt(5)
	v_add_co_u32_e32 v16, vcc, s24, v6
	v_readlane_b32 s54, v254, 13
	s_waitcnt vmcnt(4)
	v_addc_co_u32_e32 v17, vcc, 0, v7, vcc
	v_add_co_u32_e32 v20, vcc, s20, v6
	v_readlane_b32 s55, v254, 14
	s_nop 0
	v_addc_co_u32_e32 v21, vcc, 0, v7, vcc
	v_add_co_u32_e32 v22, vcc, s25, v6
	v_readlane_b32 s56, v254, 15
	s_nop 0
	v_addc_co_u32_e32 v23, vcc, 0, v7, vcc
	v_add_co_u32_e32 v24, vcc, s28, v6
	v_readlane_b32 s57, v254, 16
	s_nop 0
	v_addc_co_u32_e32 v25, vcc, 0, v7, vcc
	global_load_dword v10, v[6:7], off
	global_load_dword v11, v[8:9], off
	s_nop 0
	global_load_dword v12, v[12:13], off
	s_nop 0
	global_load_dword v13, v[14:15], off
	s_nop 0
	global_load_dword v14, v[16:17], off
	global_load_dword v15, v[20:21], off
	s_nop 0
	global_load_dword v16, v[22:23], off
	global_load_dword v17, v[24:25], off
	v_ashrrev_i32_e32 v6, 5, v4
	v_lshlrev_b32_e32 v4, 1, v4
	v_and_b32_e32 v4, 62, v4
	v_add_u32_e32 v9, 0, v0
	v_lshlrev_b32_e32 v0, 1, v4
	v_mul_u32_u24_e32 v7, 0x104, v4
	v_lshl_add_u64 v[4:5], s[0:1], 0, v[0:1]
	v_lshlrev_b32_e32 v0, 2, v6
	v_add3_u32 v7, 0, v7, v0
	v_mul_lo_u32 v0, v19, s29
	v_add_u32_e32 v8, s11, v19
	v_add_u32_e32 v9, v9, v0
	v_lshlrev_b32_e32 v0, 2, v18
	v_readlane_b32 s58, v254, 17
	v_readlane_b32 s59, v254, 18
	v_readlane_b32 s60, v254, 19
	v_readlane_b32 s61, v254, 20
	v_readlane_b32 s62, v254, 21
	v_readlane_b32 s63, v254, 22
	v_readlane_b32 s64, v254, 23
	v_readlane_b32 s65, v254, 24
	s_branch .LBB0_389

; #define LAS __attribute__((address_space(3)))
; __device__ __forceinline__ int tid_opaque() { int t = threadIdx.x; asm volatile("" : "+v"(t)); return t; }
; __device__ __forceinline__ int bid_opaque() { int b = blockIdx.x; asm volatile("" : "+s"(b)); return b; }
; __device__ __forceinline__ void tr_job(LAS float* tl, const float* src, int ld_src, int K, int Nout, bf16_t* dst, int ld_dst, int dkofs, int mode) {
;     const int tid = tid_opaque();
;     const int nkt = K / 64, ntl = nkt * (Nout / 64), G = gridDim.x;
;     const int ln = tid & 63, lk = tid >> 6, sk2 = (tid & 31) * 2, sn = tid >> 5;
;     float r[8];
;     int t = bid_opaque();
;     auto src_ptr = [&](int tt) -> const float* {
;         const int kt = tt % nkt, n0 = (tt / nkt) * 64; int c0 = n0;
;         if (mode == 1) { const int pn = n0 >> 8, rr = n0 & 255; c0 = (rr < 128) ? pn * 128 + rr : DFF + pn * 128 + (rr - 128); }
;         return src + (size_t)(kt * 64 + lk) * ld_src + c0 + ln; };
;     if (t < ntl) { const float* sp = src_ptr(t);
; #pragma unroll
;         for (int i = 0; i < 8; ++i) r[i] = sp[(size_t)(8 * i) * ld_src]; }
;     for (; t < ntl; t += G) {
; #pragma unroll
;         for (int i = 0; i < 8; ++i) tl[(lk + 8 * i) * 65 + ln] = r[i];
;         __syncthreads();
;         if (t + G < ntl) { const float* sp = src_ptr(t + G);
; #pragma unroll
;             for (int i = 0; i < 8; ++i) r[i] = sp[(size_t)(8 * i) * ld_src]; }
; __device__ void phase_setup(const Params& p, LAS unsigned char* lds) {
;     ...
;             tr_job(tl, p.in[I_FFNOUT] + ((size_t)l * 2 + j) * DFF * D, D, DFF, D, W + (j ? W_FOUT1 : W_FOUT0), DFF, 0, 0);
.LBB0_392:
	v_mov_b32_e32 v4, v218
	s_mov_b32 s8, s2
	s_cmpk_gt_i32 s8, 0x2bf
	s_branch .LBB0_397
	s_mul_i32 s4, s86, 0x1600000
	s_mul_hi_u32 s5, s86, 0x1600000
	s_add_u32 s4, s52, s4
	s_mul_hi_i32 s6, s8, 0x2e8ba2e9
	s_addc_u32 s5, s53, s5
	s_lshr_b32 s7, s6, 31
	s_ashr_i32 s6, s6, 3
	s_add_i32 s7, s6, s7
	s_lshl_b32 s6, s7, 6
	s_mul_i32 s7, s7, 44
	v_ashrrev_i32_e32 v19, 6, v4
	s_sub_i32 s7, s8, s7
	v_lshl_add_u32 v6, s7, 6, v19
	v_ashrrev_i32_e32 v7, 31, v6
	v_lshlrev_b64 v[6:7], 12, v[6:7]
	v_and_b32_e32 v18, 63, v4
	v_lshl_add_u64 v[6:7], s[4:5], 0, v[6:7]
	s_ashr_i32 s7, s6, 31
	v_lshl_add_u64 v[6:7], s[6:7], 2, v[6:7]
	v_lshlrev_b32_e32 v0, 2, v18
	v_lshl_add_u64 v[6:7], v[6:7], 0, v[0:1]
	v_add_co_u32_e32 v8, vcc, s90, v6
	s_mov_b64 s[6:7], 0x1600000
	s_nop 0
	v_addc_co_u32_e32 v9, vcc, 0, v7, vcc
	s_waitcnt vmcnt(0)
	v_add_co_u32_e32 v12, vcc, s33, v6
	s_waitcnt lgkmcnt(0)
	s_lshl_b32 s11, s10, 6
	v_addc_co_u32_e32 v13, vcc, 0, v7, vcc
	v_add_co_u32_e32 v14, vcc, s3, v6
	s_lshl_b32 s9, s8, 6
	s_nop 0
	v_addc_co_u32_e32 v15, vcc, 0, v7, vcc
	v_add_co_u32_e32 v16, vcc, s40, v6
	s_nop 1
	v_addc_co_u32_e32 v17, vcc, 0, v7, vcc
	v_add_co_u32_e32 v20, vcc, s51, v6
	s_nop 1
	v_addc_co_u32_e32 v21, vcc, 0, v7, vcc
	v_add_co_u32_e32 v22, vcc, s30, v6
	s_nop 1
	v_addc_co_u32_e32 v23, vcc, 0, v7, vcc
	v_add_co_u32_e32 v24, vcc, s31, v6
	s_nop 1
	v_addc_co_u32_e32 v25, vcc, 0, v7, vcc
	global_load_dword v10, v[6:7], off
	global_load_dword v11, v[8:9], off
	s_nop 0
	global_load_dword v12, v[12:13], off
	s_nop 0
	global_load_dword v13, v[14:15], off
	s_nop 0
	global_load_dword v14, v[16:17], off
	global_load_dword v15, v[20:21], off
	s_nop 0
	global_load_dword v16, v[22:23], off
	global_load_dword v17, v[24:25], off
	v_ashrrev_i32_e32 v6, 5, v4
	v_lshlrev_b32_e32 v4, 1, v4
	v_and_b32_e32 v4, 62, v4
	v_add_u32_e32 v9, 0, v0
	v_lshlrev_b32_e32 v0, 1, v4
	v_mul_u32_u24_e32 v7, 0x104, v4
	v_lshl_add_u64 v[4:5], s[0:1], 0, v[0:1]
	v_lshlrev_b32_e32 v0, 2, v6
	v_add3_u32 v7, 0, v7, v0
	v_mul_lo_u32 v0, v19, s29
	v_lshl_add_u64 v[4:5], v[4:5], 0, s[6:7]
	v_add_u32_e32 v8, s11, v19
	v_add_u32_e32 v9, v9, v0
	v_lshlrev_b32_e32 v0, 2, v18
	s_branch .LBB0_395

; #define LAS __attribute__((address_space(3)))
; __device__ __forceinline__ int tid_opaque() { int t = threadIdx.x; asm volatile("" : "+v"(t)); return t; }
; __device__ __forceinline__ int bid_opaque() { int b = blockIdx.x; asm volatile("" : "+s"(b)); return b; }
; __device__ __forceinline__ void tr_job(LAS float* tl, const float* src, int ld_src, int K, int Nout, bf16_t* dst, int ld_dst, int dkofs, int mode) {
;     const int tid = tid_opaque();
;     const int nkt = K / 64, ntl = nkt * (Nout / 64), G = gridDim.x;
;     const int ln = tid & 63, lk = tid >> 6, sk2 = (tid & 31) * 2, sn = tid >> 5;
;     float r[8];
;     int t = bid_opaque();
;     auto src_ptr = [&](int tt) -> const float* {
;         const int kt = tt % nkt, n0 = (tt / nkt) * 64; int c0 = n0;
;         if (mode == 1) { const int pn = n0 >> 8, rr = n0 & 255; c0 = (rr < 128) ? pn * 128 + rr : DFF + pn * 128 + (rr - 128); }
;         return src + (size_t)(kt * 64 + lk) * ld_src + c0 + ln; };
;     if (t < ntl) { const float* sp = src_ptr(t);
; #pragma unroll
;         for (int i = 0; i < 8; ++i) r[i] = sp[(size_t)(8 * i) * ld_src]; }
;     for (; t < ntl; t += G) {
; #pragma unroll
;         for (int i = 0; i < 8; ++i) tl[(lk + 8 * i) * 65 + ln] = r[i];
;         __syncthreads();
;         if (t + G < ntl) { const float* sp = src_ptr(t + G);
; #pragma unroll
;             for (int i = 0; i < 8; ++i) r[i] = sp[(size_t)(8 * i) * ld_src]; }
; __device__ void phase_setup(const Params& p, LAS unsigned char* lds) {
;     ...
;             tr_job(tl, p.in[I_FFNIN] + ((size_t)l * 2 + j) * D * (2 * DFF), 2 * DFF, D, 2 * DFF, W + (j ? W_FIN1 : W_FIN0), D, 0, 1);
.LBB0_397:
	s_lshl_b64 s[4:5], s[86:87], 1
	s_or_b32 s4, s4, 1
	v_mov_b32_e32 v4, v218
	s_mov_b32 s11, s2
	s_cmpk_gt_i32 s11, 0x57f
	s_branch .LBB0_403
	s_mul_i32 s6, s5, 0x1600000
	s_mul_hi_u32 s7, s4, 0x1600000
	v_readlane_b32 s52, v254, 11
	s_add_i32 s7, s7, s6
	s_mul_i32 s6, s4, 0x1600000
	v_readlane_b32 s66, v254, 25
	v_readlane_b32 s67, v254, 26
	s_add_u32 s6, s66, s6
	s_addc_u32 s7, s67, s7
	s_ashr_i32 s8, s11, 31
	s_lshr_b32 s8, s8, 28
	s_add_i32 s9, s11, s8
	s_ashr_i32 s8, s9, 4
	s_lshl_b32 s12, s8, 6
	s_lshl_b32 s8, s8, 5
	s_and_b32 s12, s12, 0xc0
	s_and_b32 s8, s8, 0xffffff80
	s_or_b32 s13, s8, s12
	s_add_i32 s8, s12, s8
	s_addk_i32 s8, 0xa80
	s_cmpk_lt_u32 s12, 0x80
	s_cselect_b32 s8, s13, s8
	s_and_b32 s9, s9, 0x3fffff0
	v_ashrrev_i32_e32 v19, 6, v4
	s_sub_i32 s9, s11, s9
	v_lshl_add_u32 v0, s9, 6, v19
	v_mov_b64_e32 v[6:7], s[6:7]
	v_and_b32_e32 v18, 63, v4
	v_mad_i64_i32 v[6:7], s[12:13], v0, s50, v[6:7]
	s_ashr_i32 s9, s8, 31
	v_lshl_add_u64 v[6:7], s[8:9], 2, v[6:7]
	v_lshlrev_b32_e32 v0, 2, v18
	v_lshl_add_u64 v[6:7], v[6:7], 0, v[0:1]
	v_add_co_u32_e32 v8, vcc, s49, v6
	s_mov_b64 s[8:9], 0xb00000
	s_nop 0
	v_addc_co_u32_e32 v9, vcc, 0, v7, vcc
	s_waitcnt vmcnt(0)
	v_add_co_u32_e32 v12, vcc, s22, v6
	s_waitcnt lgkmcnt(0)
	s_lshl_b32 s13, s10, 6
	v_addc_co_u32_e32 v13, vcc, 0, v7, vcc
	v_add_co_u32_e32 v14, vcc, s23, v6
	s_lshl_b32 s12, s11, 6
	s_nop 0
	v_addc_co_u32_e32 v15, vcc, 0, v7, vcc
	v_add_co_u32_e32 v16, vcc, s24, v6
	v_readlane_b32 s53, v254, 12
	s_nop 0
	v_addc_co_u32_e32 v17, vcc, 0, v7, vcc
	v_add_co_u32_e32 v20, vcc, s20, v6
	v_readlane_b32 s54, v254, 13
	s_nop 0
	v_addc_co_u32_e32 v21, vcc, 0, v7, vcc
	v_add_co_u32_e32 v22, vcc, s25, v6
	v_readlane_b32 s55, v254, 14
	s_nop 0
	v_addc_co_u32_e32 v23, vcc, 0, v7, vcc
	v_add_co_u32_e32 v24, vcc, s28, v6
	v_readlane_b32 s56, v254, 15
	s_nop 0
	v_addc_co_u32_e32 v25, vcc, 0, v7, vcc
	global_load_dword v10, v[6:7], off
	global_load_dword v11, v[8:9], off
	s_nop 0
	global_load_dword v12, v[12:13], off
	s_nop 0
	global_load_dword v13, v[14:15], off
	s_nop 0
	global_load_dword v14, v[16:17], off
	global_load_dword v15, v[20:21], off
	s_nop 0
	global_load_dword v16, v[22:23], off
	global_load_dword v17, v[24:25], off
	v_ashrrev_i32_e32 v6, 5, v4
	v_lshlrev_b32_e32 v4, 1, v4
	v_and_b32_e32 v4, 62, v4
	v_add_u32_e32 v9, 0, v0
	v_lshlrev_b32_e32 v0, 1, v4
	v_mul_u32_u24_e32 v7, 0x104, v4
	v_lshl_add_u64 v[4:5], s[0:1], 0, v[0:1]
	v_lshlrev_b32_e32 v0, 2, v6
	v_add3_u32 v7, 0, v7, v0
	v_mul_lo_u32 v0, v19, s29
	v_lshl_add_u64 v[4:5], v[4:5], 0, s[8:9]
	v_add_u32_e32 v8, s13, v19
	v_add_u32_e32 v9, v9, v0
	v_lshlrev_b32_e32 v0, 2, v18
	v_readlane_b32 s57, v254, 16
	v_readlane_b32 s58, v254, 17
	v_readlane_b32 s59, v254, 18
	v_readlane_b32 s60, v254, 19
	v_readlane_b32 s61, v254, 20
	v_readlane_b32 s62, v254, 21
	v_readlane_b32 s63, v254, 22
	v_readlane_b32 s64, v254, 23
	v_readlane_b32 s65, v254, 24
	s_branch .LBB0_400

; #define LAS __attribute__((address_space(3)))
; __device__ __forceinline__ int tid_opaque() { int t = threadIdx.x; asm volatile("" : "+v"(t)); return t; }
; __device__ __forceinline__ int bid_opaque() { int b = blockIdx.x; asm volatile("" : "+s"(b)); return b; }
; __device__ __forceinline__ void tr_job(LAS float* tl, const float* src, int ld_src, int K, int Nout, bf16_t* dst, int ld_dst, int dkofs, int mode) {
;     const int tid = tid_opaque();
;     const int nkt = K / 64, ntl = nkt * (Nout / 64), G = gridDim.x;
;     const int ln = tid & 63, lk = tid >> 6, sk2 = (tid & 31) * 2, sn = tid >> 5;
;     float r[8];
;     int t = bid_opaque();
;     auto src_ptr = [&](int tt) -> const float* {
;         const int kt = tt % nkt, n0 = (tt / nkt) * 64; int c0 = n0;
;         if (mode == 1) { const int pn = n0 >> 8, rr = n0 & 255; c0 = (rr < 128) ? pn * 128 + rr : DFF + pn * 128 + (rr - 128); }
;         return src + (size_t)(kt * 64 + lk) * ld_src + c0 + ln; };
;     if (t < ntl) { const float* sp = src_ptr(t);
; #pragma unroll
;         for (int i = 0; i < 8; ++i) r[i] = sp[(size_t)(8 * i) * ld_src]; }
;     for (; t < ntl; t += G) {
; #pragma unroll
;         for (int i = 0; i < 8; ++i) tl[(lk + 8 * i) * 65 + ln] = r[i];
;         __syncthreads();
;         if (t + G < ntl) { const float* sp = src_ptr(t + G);
; #pragma unroll
;             for (int i = 0; i < 8; ++i) r[i] = sp[(size_t)(8 * i) * ld_src]; }
; __device__ void phase_setup(const Params& p, LAS unsigned char* lds) {
;     ...
;             tr_job(tl, p.in[I_FFNOUT] + ((size_t)l * 2 + j) * DFF * D, D, DFF, D, W + (j ? W_FOUT1 : W_FOUT0), DFF, 0, 0);
.LBB0_403:
	v_mov_b32_e32 v4, v218
	s_mov_b32 s8, s2
	s_cmpk_gt_i32 s8, 0x2bf
	s_branch .LBB0_408
	s_mul_i32 s5, s5, 0xb00000
	s_mul_hi_u32 s6, s4, 0xb00000
	s_add_i32 s6, s6, s5
	s_mul_i32 s4, s4, 0xb00000
	s_add_u32 s4, s52, s4
	s_addc_u32 s5, s53, s6
	s_mul_hi_i32 s6, s8, 0x2e8ba2e9
	s_lshr_b32 s7, s6, 31
	s_ashr_i32 s6, s6, 3
	s_add_i32 s7, s6, s7
	s_lshl_b32 s6, s7, 6
	s_mul_i32 s7, s7, 44
	v_ashrrev_i32_e32 v19, 6, v4
	s_sub_i32 s7, s8, s7
	v_lshl_add_u32 v6, s7, 6, v19
	v_ashrrev_i32_e32 v7, 31, v6
	v_lshlrev_b64 v[6:7], 12, v[6:7]
	v_and_b32_e32 v18, 63, v4
	v_lshl_add_u64 v[6:7], s[4:5], 0, v[6:7]
	s_ashr_i32 s7, s6, 31
	v_lshl_add_u64 v[6:7], s[6:7], 2, v[6:7]
	v_lshlrev_b32_e32 v0, 2, v18
	v_lshl_add_u64 v[6:7], v[6:7], 0, v[0:1]
	v_add_co_u32_e32 v8, vcc, s90, v6
	s_mov_b64 s[6:7], 0x1b80000
	s_nop 0
	v_addc_co_u32_e32 v9, vcc, 0, v7, vcc
	s_waitcnt vmcnt(0)
	v_add_co_u32_e32 v12, vcc, s33, v6
	s_waitcnt lgkmcnt(0)
	s_lshl_b32 s11, s10, 6
	v_addc_co_u32_e32 v13, vcc, 0, v7, vcc
	v_add_co_u32_e32 v14, vcc, s3, v6
	s_lshl_b32 s9, s8, 6
	s_nop 0
	v_addc_co_u32_e32 v15, vcc, 0, v7, vcc
	v_add_co_u32_e32 v16, vcc, s40, v6
	s_nop 1
	v_addc_co_u32_e32 v17, vcc, 0, v7, vcc
	v_add_co_u32_e32 v20, vcc, s51, v6
	s_nop 1
	v_addc_co_u32_e32 v21, vcc, 0, v7, vcc
	v_add_co_u32_e32 v22, vcc, s30, v6
	s_nop 1
	v_addc_co_u32_e32 v23, vcc, 0, v7, vcc
	v_add_co_u32_e32 v24, vcc, s31, v6
	s_nop 1
	v_addc_co_u32_e32 v25, vcc, 0, v7, vcc
	global_load_dword v10, v[6:7], off
	global_load_dword v11, v[8:9], off
	s_nop 0
	global_load_dword v12, v[12:13], off
	s_nop 0
	global_load_dword v13, v[14:15], off
	s_nop 0
	global_load_dword v14, v[16:17], off
	global_load_dword v15, v[20:21], off
	s_nop 0
	global_load_dword v16, v[22:23], off
	global_load_dword v17, v[24:25], off
	v_ashrrev_i32_e32 v6, 5, v4
	v_lshlrev_b32_e32 v4, 1, v4
	v_and_b32_e32 v4, 62, v4
	v_add_u32_e32 v9, 0, v0
	v_lshlrev_b32_e32 v0, 1, v4
	v_mul_u32_u24_e32 v7, 0x104, v4
	v_lshl_add_u64 v[4:5], s[0:1], 0, v[0:1]
	v_lshlrev_b32_e32 v0, 2, v6
	v_add3_u32 v7, 0, v7, v0
	v_mul_lo_u32 v0, v19, s29
	v_lshl_add_u64 v[4:5], v[4:5], 0, s[6:7]
	v_add_u32_e32 v8, s11, v19
	v_add_u32_e32 v9, v9, v0
	v_lshlrev_b32_e32 v0, 2, v18
	s_branch .LBB0_406

; #define LAS __attribute__((address_space(3)))
; __device__ __forceinline__ int tid_opaque() { int t = threadIdx.x; asm volatile("" : "+v"(t)); return t; }
; __device__ __forceinline__ int bid_opaque() { int b = blockIdx.x; asm volatile("" : "+s"(b)); return b; }
; __device__ __forceinline__ void tr_job(LAS float* tl, const float* src, int ld_src, int K, int Nout, bf16_t* dst, int ld_dst, int dkofs, int mode) {
;     const int tid = tid_opaque();
;     const int nkt = K / 64, ntl = nkt * (Nout / 64), G = gridDim.x;
;     const int ln = tid & 63, lk = tid >> 6, sk2 = (tid & 31) * 2, sn = tid >> 5;
;     float r[8];
;     int t = bid_opaque();
;     auto src_ptr = [&](int tt) -> const float* {
;         const int kt = tt % nkt, n0 = (tt / nkt) * 64; int c0 = n0;
;         if (mode == 1) { const int pn = n0 >> 8, rr = n0 & 255; c0 = (rr < 128) ? pn * 128 + rr : DFF + pn * 128 + (rr - 128); }
;         return src + (size_t)(kt * 64 + lk) * ld_src + c0 + ln; };
;     if (t < ntl) { const float* sp = src_ptr(t);
; #pragma unroll
;         for (int i = 0; i < 8; ++i) r[i] = sp[(size_t)(8 * i) * ld_src]; }
;     for (; t < ntl; t += G) {
; #pragma unroll
;         for (int i = 0; i < 8; ++i) tl[(lk + 8 * i) * 65 + ln] = r[i];
;         __syncthreads();
;         if (t + G < ntl) { const float* sp = src_ptr(t + G);
; #pragma unroll
;             for (int i = 0; i < 8; ++i) r[i] = sp[(size_t)(8 * i) * ld_src]; }
; __device__ void phase_setup(const Params& p, LAS unsigned char* lds) {
;     ...
;         tr_job(tl, p.in[I_WIN] + (size_t)l * D * PROJ, PROJ, D, PROJ, W + W_WIN, D, 0, 0);
.LBB0_408:
	v_mov_b32_e32 v4, v218
	s_mov_b32 s8, s2
	s_cmpk_lt_i32 s8, 0x500
	s_branch .LBB0_413
	s_mul_i32 s4, s86, 0x1400000
	s_mul_hi_u32 s5, s86, 0x1400000
	s_add_u32 s4, s54, s4
	s_addc_u32 s5, s55, s5
	s_ashr_i32 s6, s8, 31
	s_lshr_b32 s6, s6, 28
	s_add_i32 s7, s8, s6
	s_lshl_b32 s6, s7, 2
	s_and_b32 s7, s7, 0x3fffff0
	v_ashrrev_i32_e32 v19, 6, v4
	s_sub_i32 s7, s8, s7
	s_andn2_b32 s6, s6, 63
	v_lshl_add_u32 v0, s7, 6, v19
	v_mov_b64_e32 v[6:7], s[4:5]
	v_and_b32_e32 v18, 63, v4
	v_mad_i64_i32 v[6:7], s[12:13], v0, s27, v[6:7]
	s_ashr_i32 s7, s6, 31
	v_lshl_add_u64 v[6:7], s[6:7], 2, v[6:7]
	v_lshlrev_b32_e32 v0, 2, v18
	v_lshl_add_u64 v[6:7], v[6:7], 0, v[0:1]
	v_add_co_u32_e32 v8, vcc, s51, v6
	s_mov_b32 s6, 0xa0000
	s_nop 0
	v_addc_co_u32_e32 v9, vcc, 0, v7, vcc
	s_waitcnt vmcnt(0)
	v_add_co_u32_e32 v12, vcc, s96, v6
	s_waitcnt lgkmcnt(0)
	s_lshl_b32 s11, s10, 6
	v_addc_co_u32_e32 v13, vcc, 0, v7, vcc
	v_add_co_u32_e32 v14, vcc, s21, v6
	s_lshl_b32 s9, s8, 6
	s_nop 0
	v_addc_co_u32_e32 v15, vcc, 0, v7, vcc
	v_add_co_u32_e32 v16, vcc, s6, v6
	s_mov_b32 s6, 0xc8000
	s_nop 0
	v_addc_co_u32_e32 v17, vcc, 0, v7, vcc
	v_add_co_u32_e32 v20, vcc, s6, v6
	s_mov_b32 s6, 0xf0000
	s_nop 0
	v_addc_co_u32_e32 v21, vcc, 0, v7, vcc
	v_add_co_u32_e32 v22, vcc, s6, v6
	s_mov_b32 s6, 0x118000
	s_nop 0
	v_addc_co_u32_e32 v23, vcc, 0, v7, vcc
	v_add_co_u32_e32 v24, vcc, s6, v6
	s_mov_b64 s[6:7], 0x2100000
	s_nop 0
	v_addc_co_u32_e32 v25, vcc, 0, v7, vcc
	global_load_dword v10, v[6:7], off
	global_load_dword v11, v[8:9], off
	s_nop 0
	global_load_dword v12, v[12:13], off
	s_nop 0
	global_load_dword v13, v[14:15], off
	s_nop 0
	global_load_dword v14, v[16:17], off
	global_load_dword v15, v[20:21], off
	s_nop 0
	global_load_dword v16, v[22:23], off
	global_load_dword v17, v[24:25], off
	v_ashrrev_i32_e32 v6, 5, v4
	v_lshlrev_b32_e32 v4, 1, v4
	v_and_b32_e32 v4, 62, v4
	v_add_u32_e32 v9, 0, v0
	v_lshlrev_b32_e32 v0, 1, v4
	v_mul_u32_u24_e32 v7, 0x104, v4
	v_lshl_add_u64 v[4:5], s[0:1], 0, v[0:1]
	v_lshlrev_b32_e32 v0, 2, v6
	v_add3_u32 v7, 0, v7, v0
	v_mul_lo_u32 v0, v19, s29
	v_lshl_add_u64 v[4:5], v[4:5], 0, s[6:7]
	v_add_u32_e32 v8, s11, v19
	v_add_u32_e32 v9, v9, v0
	v_lshlrev_b32_e32 v0, 2, v18
	s_branch .LBB0_411

; #define LAS __attribute__((address_space(3)))
; __device__ __forceinline__ int tid_opaque() { int t = threadIdx.x; asm volatile("" : "+v"(t)); return t; }
; __device__ __forceinline__ int bid_opaque() { int b = blockIdx.x; asm volatile("" : "+s"(b)); return b; }
; __device__ __forceinline__ void tr_job(LAS float* tl, const float* src, int ld_src, int K, int Nout, bf16_t* dst, int ld_dst, int dkofs, int mode) {
;     const int tid = tid_opaque();
;     const int nkt = K / 64, ntl = nkt * (Nout / 64), G = gridDim.x;
;     const int ln = tid & 63, lk = tid >> 6, sk2 = (tid & 31) * 2, sn = tid >> 5;
;     float r[8];
;     int t = bid_opaque();
;     auto src_ptr = [&](int tt) -> const float* {
;         const int kt = tt % nkt, n0 = (tt / nkt) * 64; int c0 = n0;
;         if (mode == 1) { const int pn = n0 >> 8, rr = n0 & 255; c0 = (rr < 128) ? pn * 128 + rr : DFF + pn * 128 + (rr - 128); }
;         return src + (size_t)(kt * 64 + lk) * ld_src + c0 + ln; };
;     if (t < ntl) { const float* sp = src_ptr(t);
; #pragma unroll
;         for (int i = 0; i < 8; ++i) r[i] = sp[(size_t)(8 * i) * ld_src]; }
;     for (; t < ntl; t += G) {
; #pragma unroll
;         for (int i = 0; i < 8; ++i) tl[(lk + 8 * i) * 65 + ln] = r[i];
;         __syncthreads();
;         if (t + G < ntl) { const float* sp = src_ptr(t + G);
; #pragma unroll
;             for (int i = 0; i < 8; ++i) r[i] = sp[(size_t)(8 * i) * ld_src]; }
; __device__ void phase_setup(const Params& p, LAS unsigned char* lds) {
;     ...
;         tr_job(tl, p.in[I_WBC] + (size_t)l * 256 * D, D, 256, D, W + W_WB, D, 0, 0);
.LBB0_413:
	s_lshl_b64 s[4:5], s[86:87], 18
	v_mov_b32_e32 v4, v218
	s_mov_b32 s11, s2
	s_cmp_gt_i32 s11, 63
	s_branch .LBB0_418
	s_lshl_b64 s[6:7], s[4:5], 2
	s_add_u32 s6, s74, s6
	s_addc_u32 s7, s75, s7
	s_ashr_i32 s8, s11, 31
	s_lshr_b32 s8, s8, 30
	s_add_i32 s9, s11, s8
	s_lshl_b32 s8, s9, 4
	s_and_b32 s9, s9, 0x3fffffc
	v_ashrrev_i32_e32 v19, 6, v4
	s_sub_i32 s9, s11, s9
	v_lshl_add_u32 v6, s9, 6, v19
	v_ashrrev_i32_e32 v7, 31, v6
	s_andn2_b32 s8, s8, 63
	v_lshlrev_b64 v[6:7], 12, v[6:7]
	v_and_b32_e32 v18, 63, v4
	v_lshl_add_u64 v[6:7], s[6:7], 0, v[6:7]
	s_ashr_i32 s9, s8, 31
	v_lshl_add_u64 v[6:7], s[8:9], 2, v[6:7]
	v_lshlrev_b32_e32 v0, 2, v18
	v_lshl_add_u64 v[6:7], v[6:7], 0, v[0:1]
	v_add_co_u32_e32 v8, vcc, s90, v6
	s_mov_b64 s[8:9], 0x2b00000
	s_nop 0
	v_addc_co_u32_e32 v9, vcc, 0, v7, vcc
	s_waitcnt vmcnt(0)
	v_add_co_u32_e32 v12, vcc, s33, v6
	s_waitcnt lgkmcnt(0)
	s_lshl_b32 s13, s10, 6
	v_addc_co_u32_e32 v13, vcc, 0, v7, vcc
	v_add_co_u32_e32 v14, vcc, s3, v6
	s_lshl_b32 s12, s11, 6
	s_nop 0
	v_addc_co_u32_e32 v15, vcc, 0, v7, vcc
	v_add_co_u32_e32 v16, vcc, s40, v6
	s_nop 1
	v_addc_co_u32_e32 v17, vcc, 0, v7, vcc
	v_add_co_u32_e32 v20, vcc, s51, v6
	s_nop 1
	v_addc_co_u32_e32 v21, vcc, 0, v7, vcc
	v_add_co_u32_e32 v22, vcc, s30, v6
	s_nop 1
	v_addc_co_u32_e32 v23, vcc, 0, v7, vcc
	v_add_co_u32_e32 v24, vcc, s31, v6
	s_nop 1
	v_addc_co_u32_e32 v25, vcc, 0, v7, vcc
	global_load_dword v10, v[6:7], off
	global_load_dword v11, v[8:9], off
	s_nop 0
	global_load_dword v12, v[12:13], off
	s_nop 0
	global_load_dword v13, v[14:15], off
	s_nop 0
	global_load_dword v14, v[16:17], off
	global_load_dword v15, v[20:21], off
	s_nop 0
	global_load_dword v16, v[22:23], off
	global_load_dword v17, v[24:25], off
	v_ashrrev_i32_e32 v6, 5, v4
	v_lshlrev_b32_e32 v4, 1, v4
	v_and_b32_e32 v4, 62, v4
	v_add_u32_e32 v9, 0, v0
	v_lshlrev_b32_e32 v0, 1, v4
	v_mul_u32_u24_e32 v7, 0x104, v4
	v_lshl_add_u64 v[4:5], s[0:1], 0, v[0:1]
	v_lshlrev_b32_e32 v0, 2, v6
	v_add3_u32 v7, 0, v7, v0
	v_mul_lo_u32 v0, v19, s29
	v_lshl_add_u64 v[4:5], v[4:5], 0, s[8:9]
	v_add_u32_e32 v8, s13, v19
	v_add_u32_e32 v9, v9, v0
	v_lshlrev_b32_e32 v0, 2, v18
	s_branch .LBB0_416

; #define LAS __attribute__((address_space(3)))
; __device__ __forceinline__ int tid_opaque() { int t = threadIdx.x; asm volatile("" : "+v"(t)); return t; }
; __device__ __forceinline__ int bid_opaque() { int b = blockIdx.x; asm volatile("" : "+s"(b)); return b; }
; __device__ __forceinline__ void tr_job(LAS float* tl, const float* src, int ld_src, int K, int Nout, bf16_t* dst, int ld_dst, int dkofs, int mode) {
;     const int tid = tid_opaque();
;     const int nkt = K / 64, ntl = nkt * (Nout / 64), G = gridDim.x;
;     const int ln = tid & 63, lk = tid >> 6, sk2 = (tid & 31) * 2, sn = tid >> 5;
;     float r[8];
;     int t = bid_opaque();
;     auto src_ptr = [&](int tt) -> const float* {
;         const int kt = tt % nkt, n0 = (tt / nkt) * 64; int c0 = n0;
;         if (mode == 1) { const int pn = n0 >> 8, rr = n0 & 255; c0 = (rr < 128) ? pn * 128 + rr : DFF + pn * 128 + (rr - 128); }
;         return src + (size_t)(kt * 64 + lk) * ld_src + c0 + ln; };
;     if (t < ntl) { const float* sp = src_ptr(t);
; #pragma unroll
;         for (int i = 0; i < 8; ++i) r[i] = sp[(size_t)(8 * i) * ld_src]; }
;     for (; t < ntl; t += G) {
; #pragma unroll
;         for (int i = 0; i < 8; ++i) tl[(lk + 8 * i) * 65 + ln] = r[i];
;         __syncthreads();
;         if (t + G < ntl) { const float* sp = src_ptr(t + G);
; #pragma unroll
;             for (int i = 0; i < 8; ++i) r[i] = sp[(size_t)(8 * i) * ld_src]; }
; __device__ void phase_setup(const Params& p, LAS unsigned char* lds) {
;     ...
;         tr_job(tl, p.in[I_WBG] + (size_t)l * 256 * D, D, 256, D, W + W_WB, D, 256, 0);
.LBB0_418:
	v_mov_b32_e32 v4, v218
	s_mov_b32 s11, s2
	s_cmp_gt_i32 s11, 63
	s_branch .LBB0_423
	s_lshl_b64 s[6:7], s[4:5], 2
	s_add_u32 s6, s76, s6
	s_addc_u32 s7, s77, s7
	s_ashr_i32 s8, s11, 31
	s_lshr_b32 s8, s8, 30
	s_add_i32 s9, s11, s8
	s_lshl_b32 s8, s9, 4
	s_and_b32 s9, s9, 0x3fffffc
	v_ashrrev_i32_e32 v19, 6, v4
	s_sub_i32 s9, s11, s9
	v_lshl_add_u32 v6, s9, 6, v19
	v_ashrrev_i32_e32 v7, 31, v6
	s_andn2_b32 s8, s8, 63
	v_lshlrev_b64 v[6:7], 12, v[6:7]
	v_and_b32_e32 v18, 63, v4
	v_lshl_add_u64 v[6:7], s[6:7], 0, v[6:7]
	s_ashr_i32 s9, s8, 31
	v_lshl_add_u64 v[6:7], s[8:9], 2, v[6:7]
	v_lshlrev_b32_e32 v0, 2, v18
	v_lshl_add_u64 v[6:7], v[6:7], 0, v[0:1]
	v_add_co_u32_e32 v8, vcc, s90, v6
	s_mov_b64 s[8:9], 0x2b00200
	s_nop 0
	v_addc_co_u32_e32 v9, vcc, 0, v7, vcc
	s_waitcnt vmcnt(0)
	v_add_co_u32_e32 v12, vcc, s33, v6
	s_waitcnt lgkmcnt(0)
	s_lshl_b32 s13, s10, 6
	v_addc_co_u32_e32 v13, vcc, 0, v7, vcc
	v_add_co_u32_e32 v14, vcc, s3, v6
	s_lshl_b32 s12, s11, 6
	s_nop 0
	v_addc_co_u32_e32 v15, vcc, 0, v7, vcc
	v_add_co_u32_e32 v16, vcc, s40, v6
	s_nop 1
	v_addc_co_u32_e32 v17, vcc, 0, v7, vcc
	v_add_co_u32_e32 v20, vcc, s51, v6
	s_nop 1
	v_addc_co_u32_e32 v21, vcc, 0, v7, vcc
	v_add_co_u32_e32 v22, vcc, s30, v6
	s_nop 1
	v_addc_co_u32_e32 v23, vcc, 0, v7, vcc
	v_add_co_u32_e32 v24, vcc, s31, v6
	s_nop 1
	v_addc_co_u32_e32 v25, vcc, 0, v7, vcc
	global_load_dword v10, v[6:7], off
	global_load_dword v11, v[8:9], off
	s_nop 0
	global_load_dword v12, v[12:13], off
	s_nop 0
	global_load_dword v13, v[14:15], off
	s_nop 0
	global_load_dword v14, v[16:17], off
	global_load_dword v15, v[20:21], off
	s_nop 0
	global_load_dword v16, v[22:23], off
	global_load_dword v17, v[24:25], off
	v_ashrrev_i32_e32 v6, 5, v4
	v_lshlrev_b32_e32 v4, 1, v4
	v_and_b32_e32 v4, 62, v4
	v_add_u32_e32 v9, 0, v0
	v_lshlrev_b32_e32 v0, 1, v4
	v_mul_u32_u24_e32 v7, 0x104, v4
	v_lshl_add_u64 v[4:5], s[0:1], 0, v[0:1]
	v_lshlrev_b32_e32 v0, 2, v6
	v_add3_u32 v7, 0, v7, v0
	v_mul_lo_u32 v0, v19, s29
	v_lshl_add_u64 v[4:5], v[4:5], 0, s[8:9]
	v_add_u32_e32 v8, s13, v19
	v_add_u32_e32 v9, v9, v0
	v_lshlrev_b32_e32 v0, 2, v18
	s_branch .LBB0_421

; #define LAS __attribute__((address_space(3)))
; __device__ __forceinline__ int tid_opaque() { int t = threadIdx.x; asm volatile("" : "+v"(t)); return t; }
; __device__ __forceinline__ int bid_opaque() { int b = blockIdx.x; asm volatile("" : "+s"(b)); return b; }
; __device__ __forceinline__ void tr_job(LAS float* tl, const float* src, int ld_src, int K, int Nout, bf16_t* dst, int ld_dst, int dkofs, int mode) {
;     const int tid = tid_opaque();
;     const int nkt = K / 64, ntl = nkt * (Nout / 64), G = gridDim.x;
;     const int ln = tid & 63, lk = tid >> 6, sk2 = (tid & 31) * 2, sn = tid >> 5;
;     float r[8];
;     int t = bid_opaque();
;     auto src_ptr = [&](int tt) -> const float* {
;         const int kt = tt % nkt, n0 = (tt / nkt) * 64; int c0 = n0;
;         if (mode == 1) { const int pn = n0 >> 8, rr = n0 & 255; c0 = (rr < 128) ? pn * 128 + rr : DFF + pn * 128 + (rr - 128); }
;         return src + (size_t)(kt * 64 + lk) * ld_src + c0 + ln; };
;     if (t < ntl) { const float* sp = src_ptr(t);
; #pragma unroll
;         for (int i = 0; i < 8; ++i) r[i] = sp[(size_t)(8 * i) * ld_src]; }
;     for (; t < ntl; t += G) {
; #pragma unroll
;         for (int i = 0; i < 8; ++i) tl[(lk + 8 * i) * 65 + ln] = r[i];
;         __syncthreads();
;         if (t + G < ntl) { const float* sp = src_ptr(t + G);
; #pragma unroll
;             for (int i = 0; i < 8; ++i) r[i] = sp[(size_t)(8 * i) * ld_src]; }
; __device__ void phase_setup(const Params& p, LAS unsigned char* lds) {
;     ...
;         tr_job(tl, p.in[I_WBA] + (size_t)l * 512 * D, D, 512, D, W + W_WB, D, 512, 0);
.LBB0_423:
	v_mov_b32_e32 v4, v218
	s_mov_b32 s11, s2
	s_cmpk_gt_i32 s11, 0x7f
	s_branch .LBB0_428
	s_lshl_b64 s[6:7], s[86:87], 21
	s_add_u32 s6, s78, s6
	s_addc_u32 s7, s79, s7
	s_ashr_i32 s8, s11, 31
	s_lshr_b32 s8, s8, 29
	s_add_i32 s9, s11, s8
	s_lshl_b32 s8, s9, 3
	s_and_b32 s9, s9, 0x3fffff8
	v_ashrrev_i32_e32 v19, 6, v4
	s_sub_i32 s9, s11, s9
	v_lshl_add_u32 v6, s9, 6, v19
	v_ashrrev_i32_e32 v7, 31, v6
	s_andn2_b32 s8, s8, 63
	v_lshlrev_b64 v[6:7], 12, v[6:7]
	v_and_b32_e32 v18, 63, v4
	v_lshl_add_u64 v[6:7], s[6:7], 0, v[6:7]
	s_ashr_i32 s9, s8, 31
	v_lshl_add_u64 v[6:7], s[8:9], 2, v[6:7]
	v_lshlrev_b32_e32 v0, 2, v18
	v_lshl_add_u64 v[6:7], v[6:7], 0, v[0:1]
	v_add_co_u32_e32 v8, vcc, s90, v6
	s_mov_b64 s[8:9], 0x2b00400
	s_nop 0
	v_addc_co_u32_e32 v9, vcc, 0, v7, vcc
	s_waitcnt vmcnt(0)
	v_add_co_u32_e32 v12, vcc, s33, v6
	s_waitcnt lgkmcnt(0)
	s_lshl_b32 s13, s10, 6
	v_addc_co_u32_e32 v13, vcc, 0, v7, vcc
	v_add_co_u32_e32 v14, vcc, s3, v6
	s_lshl_b32 s12, s11, 6
	s_nop 0
	v_addc_co_u32_e32 v15, vcc, 0, v7, vcc
	v_add_co_u32_e32 v16, vcc, s40, v6
	s_nop 1
	v_addc_co_u32_e32 v17, vcc, 0, v7, vcc
	v_add_co_u32_e32 v20, vcc, s51, v6
	s_nop 1
	v_addc_co_u32_e32 v21, vcc, 0, v7, vcc
	v_add_co_u32_e32 v22, vcc, s30, v6
	s_nop 1
	v_addc_co_u32_e32 v23, vcc, 0, v7, vcc
	v_add_co_u32_e32 v24, vcc, s31, v6
	s_nop 1
	v_addc_co_u32_e32 v25, vcc, 0, v7, vcc
	global_load_dword v10, v[6:7], off
	global_load_dword v11, v[8:9], off
	s_nop 0
	global_load_dword v12, v[12:13], off
	s_nop 0
	global_load_dword v13, v[14:15], off
	s_nop 0
	global_load_dword v14, v[16:17], off
	global_load_dword v15, v[20:21], off
	s_nop 0
	global_load_dword v16, v[22:23], off
	global_load_dword v17, v[24:25], off
	v_ashrrev_i32_e32 v6, 5, v4
	v_lshlrev_b32_e32 v4, 1, v4
	v_and_b32_e32 v4, 62, v4
	v_add_u32_e32 v9, 0, v0
	v_lshlrev_b32_e32 v0, 1, v4
	v_mul_u32_u24_e32 v7, 0x104, v4
	v_lshl_add_u64 v[4:5], s[0:1], 0, v[0:1]
	v_lshlrev_b32_e32 v0, 2, v6
	v_add3_u32 v7, 0, v7, v0
	v_mul_lo_u32 v0, v19, s29
	v_lshl_add_u64 v[4:5], v[4:5], 0, s[8:9]
	v_add_u32_e32 v8, s13, v19
	v_add_u32_e32 v9, v9, v0
	v_lshlrev_b32_e32 v0, 2, v18
	s_branch .LBB0_426

; #define LAS __attribute__((address_space(3)))
; __device__ __forceinline__ int tid_opaque() { int t = threadIdx.x; asm volatile("" : "+v"(t)); return t; }
; __device__ __forceinline__ int bid_opaque() { int b = blockIdx.x; asm volatile("" : "+s"(b)); return b; }
; __device__ __forceinline__ void tr_job(LAS float* tl, const float* src, int ld_src, int K, int Nout, bf16_t* dst, int ld_dst, int dkofs, int mode) {
;     const int tid = tid_opaque();
;     const int nkt = K / 64, ntl = nkt * (Nout / 64), G = gridDim.x;
;     const int ln = tid & 63, lk = tid >> 6, sk2 = (tid & 31) * 2, sn = tid >> 5;
;     float r[8];
;     int t = bid_opaque();
;     auto src_ptr = [&](int tt) -> const float* {
;         const int kt = tt % nkt, n0 = (tt / nkt) * 64; int c0 = n0;
;         if (mode == 1) { const int pn = n0 >> 8, rr = n0 & 255; c0 = (rr < 128) ? pn * 128 + rr : DFF + pn * 128 + (rr - 128); }
;         return src + (size_t)(kt * 64 + lk) * ld_src + c0 + ln; };
;     if (t < ntl) { const float* sp = src_ptr(t);
; #pragma unroll
;         for (int i = 0; i < 8; ++i) r[i] = sp[(size_t)(8 * i) * ld_src]; }
;     for (; t < ntl; t += G) {
; #pragma unroll
;         for (int i = 0; i < 8; ++i) tl[(lk + 8 * i) * 65 + ln] = r[i];
;         __syncthreads();
;         if (t + G < ntl) { const float* sp = src_ptr(t + G);
; #pragma unroll
;             for (int i = 0; i < 8; ++i) r[i] = sp[(size_t)(8 * i) * ld_src]; }
; __device__ void phase_setup(const Params& p, LAS unsigned char* lds) {
;     ...
;         tr_job(tl, p.in[I_WOUT] + (size_t)l * D * D, D, D, D, W + W_WO, D, 0, 0);
.LBB0_428:
	v_mov_b32_e32 v4, v218
	s_mov_b32 s11, s2
	s_cmpk_gt_i32 s11, 0xff
	s_branch .LBB0_433
	s_lshl_b64 s[6:7], s[86:87], 22
	s_add_u32 s6, s80, s6
	s_addc_u32 s7, s81, s7
	s_ashr_i32 s8, s11, 31
	s_lshr_b32 s8, s8, 28
	s_add_i32 s9, s11, s8
	s_lshl_b32 s8, s9, 2
	s_and_b32 s9, s9, 0x3fffff0
	v_ashrrev_i32_e32 v19, 6, v4
	s_sub_i32 s9, s11, s9
	v_lshl_add_u32 v6, s9, 6, v19
	v_ashrrev_i32_e32 v7, 31, v6
	s_andn2_b32 s8, s8, 63
	v_lshlrev_b64 v[6:7], 12, v[6:7]
	v_and_b32_e32 v18, 63, v4
	v_lshl_add_u64 v[6:7], s[6:7], 0, v[6:7]
	s_ashr_i32 s9, s8, 31
	v_lshl_add_u64 v[6:7], s[8:9], 2, v[6:7]
	v_lshlrev_b32_e32 v0, 2, v18
	v_lshl_add_u64 v[6:7], v[6:7], 0, v[0:1]
	v_add_co_u32_e32 v8, vcc, s90, v6
	s_mov_b64 s[8:9], 0x2d00000
	s_nop 0
	v_addc_co_u32_e32 v9, vcc, 0, v7, vcc
	s_waitcnt vmcnt(0)
	v_add_co_u32_e32 v12, vcc, s33, v6
	s_waitcnt lgkmcnt(0)
	s_lshl_b32 s13, s10, 6
	v_addc_co_u32_e32 v13, vcc, 0, v7, vcc
	v_add_co_u32_e32 v14, vcc, s3, v6
	s_lshl_b32 s12, s11, 6
	s_nop 0
	v_addc_co_u32_e32 v15, vcc, 0, v7, vcc
	v_add_co_u32_e32 v16, vcc, s40, v6
	s_nop 1
	v_addc_co_u32_e32 v17, vcc, 0, v7, vcc
	v_add_co_u32_e32 v20, vcc, s51, v6
	s_nop 1
	v_addc_co_u32_e32 v21, vcc, 0, v7, vcc
	v_add_co_u32_e32 v22, vcc, s30, v6
	s_nop 1
	v_addc_co_u32_e32 v23, vcc, 0, v7, vcc
	v_add_co_u32_e32 v24, vcc, s31, v6
	s_nop 1
	v_addc_co_u32_e32 v25, vcc, 0, v7, vcc
	global_load_dword v10, v[6:7], off
	global_load_dword v11, v[8:9], off
	s_nop 0
	global_load_dword v12, v[12:13], off
	s_nop 0
	global_load_dword v13, v[14:15], off
	s_nop 0
	global_load_dword v14, v[16:17], off
	global_load_dword v15, v[20:21], off
	s_nop 0
	global_load_dword v16, v[22:23], off
	global_load_dword v17, v[24:25], off
	v_ashrrev_i32_e32 v6, 5, v4
	v_lshlrev_b32_e32 v4, 1, v4
	v_and_b32_e32 v4, 62, v4
	v_add_u32_e32 v9, 0, v0
	v_lshlrev_b32_e32 v0, 1, v4
	v_mul_u32_u24_e32 v7, 0x104, v4
	v_lshl_add_u64 v[4:5], s[0:1], 0, v[0:1]
	v_lshlrev_b32_e32 v0, 2, v6
	v_add3_u32 v7, 0, v7, v0
	v_mul_lo_u32 v0, v19, s29
	v_lshl_add_u64 v[4:5], v[4:5], 0, s[8:9]
	v_add_u32_e32 v8, s13, v19
	v_add_u32_e32 v9, v9, v0
	v_lshlrev_b32_e32 v0, 2, v18
	s_branch .LBB0_431

; __device__ void run_phase(const Params& p, int ph, LAS unsigned char* lds) {
;     ...
;     const int q = ph - 1, l = q / 17, r = q % 17;
;     const bf16_t* W = (const bf16_t*)(p.ws + WS_WT) + (size_t)l * W_LAYER;
;     const float* MOD = (const float*)(p.ws + WS_MOD) + (size_t)l * 33 * (NMOD * D);
;     bf16_t* HB = (bf16_t*)(p.ws + WS_H);
;     const bool first = (l == 0 && r <= 2);
;     const bool lastl = (l == NL - 1);
;     bf16_t* A = (bf16_t*)(p.ws + WS_A); bf16_t* R1 = (bf16_t*)(p.ws + WS_R1);
;     if (r == 0 || r == 3 || r == 14) {
;     ...
;  if (l == 0 && r == 0) phase_norm(p, l, 0, true, false);
;     ...
;  return; }
;     if (r == 1 || r == 15) {
;         const int j = (r == 1) ? 0 : 1;
;         const int sk = (lastl && j == 1) ? 1 : 0;
;         pg8::Gemm g{A, D, W + (j ? W_FIN1 : W_FIN0), D, sk ? T_LAT : T_ALL, 2 * DFF, D, sk, 0};
;         pg8::EpiSwiglu E{R1};
;     ...
;         pg8::gemm_phase(lds, g, E);
;     ...
;         return;
;     }
;     if (r == 2 || r == 16) {
;         const int j = (r == 2) ? 0 : 1;
;         const int sk = (lastl && j == 1) ? 1 : 0;
;         pg8::Gemm g{R1, DFF, W + (j ? W_FOUT1 : W_FOUT0), DFF, sk ? T_LAT : T_ALL, D, DFF, sk, 1};
;         const int nj = (r == 2) ? 1 : (lastl ? -1 : 0), ln = (r == 2) ? l : l + 1;
;         const bool fin = (lastl && r == 16);
;         const float* ngp = p.in[I_NORMG] + ((size_t)(nj < 0 ? 0 : ln) * 3 + (nj < 0 ? 0 : nj)) * D; const float* nmp = (const float*)(p.ws + WS_MOD) + (size_t)(nj < 0 ? 0 : ln) * 33 * (NMOD * D);
;         unsigned* cntp = (unsigned*)(p.ws + WS_CNT) + (size_t)(l * 3 + (r == 2 ? 0 : 2)) * 576;
.LBB0_466:
	v_readlane_b32 s11, v254, 30
	s_cmp_lt_i32 s11, 1
	s_cbranch_scc1 .Lmytr_skipB
	s_add_i32 s0, s11, -1
	s_mul_hi_i32 s1, s0, 0x78787879
	s_lshr_b32 s4, s1, 31
	s_ashr_i32 s1, s1, 3
	s_add_i32 s1, s1, s4
	s_mul_i32 s4, s1, 17
	s_sub_i32 s0, s0, s4
	s_cmp_eq_u32 s0, 2
	s_cbranch_scc0 .Lmytr_skipB
	s_cmp_lt_u32 s1, 3
	s_cbranch_scc0 .Lmytr_skipB
	s_cmp_ge_u32 s2, 128
	s_cbranch_scc0 .Lmytr_skipB
	v_readlane_b32 s94, v254, 9
	v_readlane_b32 s95, v254, 10
	s_nop 3
	s_load_dword s10, s[94:95], 0x0
	s_waitcnt lgkmcnt(0)
	s_cmp_eq_u32 s10, 256
	s_cbranch_scc0 .Lmytr_skipB
	s_add_u32 s1, s1, 1
	s_mul_i32 s15, s1, 6016
	s_add_u32 s11, s15, s2
	s_sub_u32 s11, s11, 128
	s_add_u32 s15, s15, 6016
	s_movk_i32 s10, 128
	s_mov_b32 s86, 1
	s_waitcnt vmcnt(0) lgkmcnt(0)
	s_barrier
	s_branch .Lmytr_entry
